# SwiGLU GEMM: next tile's first 8 LDS-DMA loads issued at the top of the current tile's epilogue (coordinates computed into dead SGPRs), DMA-less copy of the setup afterwards; plus hgrn_out state-part
# speedup vs baseline: 1.0292x; 1.0026x over previous
; DI float sigmoidf_(float x) { return frcp(1.f + __expf(-x)); }
; #define G_STAGE(bufoff, gbase, voff) do { _Pragma("unroll") for (int _i = 0; _i < 2; ++_i) \
;     __builtin_amdgcn_global_load_lds((const unsigned*)(uniform_ptr((const char*)(gbase)) + (voff)[_i]), (LAS unsigned*)(lds + (bufoff) + ldsw + _i * 8192), 16, 0, 0); } while (0)
; DI void st_bf16x4(bf16_t* p, f32x4 v) { u32x2 o; o.x = pk2e(v[0], v[1]); o.y = pk2e(v[2], v[3]); *(u32x2*)p = o; }
;   DI float operator()(int row, int colbase, int fq, f32x4 v0, f32x4 v1) const { one(row, colbase + 4 * fq, v0); one(row, colbase + 16 + 4 * fq, v1); return 0.f; }
;     ...
;   const int nM = M / BM, nN = N / BM, nwg = nM * nN;
;   for (int u = (int)((blockIdx.x + gridDim.x - blk_off) % gridDim.x); u < nwg; u += gridDim.x) {
;     int wgid = u;
;     { int q = nwg / NXCD, r = nwg % NXCD, xcd = wgid % NXCD, off = wgid / NXCD; wgid = (xcd < r ? xcd * (q + 1) : r * (q + 1) + (xcd - r) * q) + off; }
;     int nig = WGM * nN, gid = wgid / nig, fm = gid * WGM, gsz = min(nM - fm, WGM);
;     const int pm = __builtin_amdgcn_readfirstlane(fm + ((wgid % nig) % gsz)), pn = __builtin_amdgcn_readfirstlane((wgid % nig) / gsz), brow = pm * BM, bcol = pn * BM;
;     f32x4 acc[2][2][4][2];
; #pragma unroll
;     for (int a = 0; a < 2; ++a)
; #pragma unroll
;       for (int b = 0; b < 2; ++b)
; #pragma unroll
;         for (int m = 0; m < 4; ++m)
; #pragma unroll
;           for (int n = 0; n < 2; ++n) acc[a][b][m][n] = (f32x4){0.f, 0.f, 0.f, 0.f};
;     bf16x8 At[4][2], B0[2][2], B1[2][2];
;     const char* cA = (const char*)A + (size_t)brow * lda * 2; const char* cB = (const char*)Bt + (size_t)bcol * ldb * 2;
;     G_STAGE(G_SB(0, 0), cB, voffB); G_STAGE(G_SA(0, 0), cA, voffA); G_STAGE(G_SB(0, 1), cB + hstepB, voffB); G_STAGE(G_SA(0, 1), cA + hstepA, voffA);
;   DI float rowscale(int row) const { const f32x4 a = *(const f32x4*)(ssp_in + (size_t)row * 8), b = *(const f32x4*)(ssp_in + (size_t)row * 8 + 4);
;     return rsqrtf((((a[0] + a[1]) + (a[2] + a[3])) + ((b[0] + b[1]) + (b[2] + b[3]))) * (1.f / D_) + EPS_); }
;   DI float operator()(int row, int colbase, int fq, f32x4 v0, f32x4 v1) const {
;     f32x4 r;
; #pragma unroll
;     for (int e = 0; e < 4; ++e) r[e] = v0[e] * sigmoidf_(v0[e]) * v1[e];
;     st_bf16x4(hid + (size_t)row * FFN_ + (colbase >> 1) + 4 * fq, r); return 0.f;
.LBB0_21:
	v_mov_b32_e32 v0, v199
	s_add_i32 s10, s10, s24
	s_mov_b32 s14, 0x800000
	v_and_or_b32 v136, v0, 15, s10
	v_ashrrev_i32_e32 v137, 31, v136
	v_lshlrev_b64 v[138:139], 5, v[136:137]
	v_lshl_add_u64 v[138:139], s[4:5], 0, v[138:139]
	s_mov_b64 s[100:101], 0x1000
	v_lshl_add_u64 v[240:241], v[138:139], 0, s[100:101]
	global_load_dwordx4 v[162:165], v[240:241], off offset:-4096
	global_load_dwordx4 v[166:169], v[240:241], off offset:-4080
	global_load_dwordx4 v[170:173], v[240:241], off offset:-3584
	global_load_dwordx4 v[174:177], v[240:241], off offset:-3568
	global_load_dwordx4 v[178:181], v[240:241], off offset:-3072
	global_load_dwordx4 v[182:185], v[240:241], off offset:-3056
	global_load_dwordx4 v[200:203], v[240:241], off offset:-2560
	global_load_dwordx4 v[204:207], v[240:241], off offset:-2544
	global_load_dwordx4 v[208:211], v[240:241], off
	global_load_dwordx4 v[212:215], v[240:241], off offset:16
	global_load_dwordx4 v[216:219], v[240:241], off offset:512
	global_load_dwordx4 v[220:223], v[240:241], off offset:528
	global_load_dwordx4 v[224:227], v[240:241], off offset:1024
	global_load_dwordx4 v[228:231], v[240:241], off offset:1040
	global_load_dwordx4 v[232:235], v[240:241], off offset:1536
	global_load_dwordx4 v[236:239], v[240:241], off offset:1552
	v_readlane_b32 s33, v250, 1
	s_add_i32 s33, s31, s33
	s_cmpk_gt_i32 s33, 0x57f
	s_cbranch_scc1 .Lpf_skip
	s_ashr_i32 s34, s33, 31
	s_lshr_b32 s34, s34, 29
	s_add_i32 s34, s33, s34
	s_ashr_i32 s35, s34, 3
	s_and_b32 s34, s34, -8
	s_sub_i32 s34, s33, s34
	s_cmp_lt_i32 s34, 0
	s_movk_i32 s36, 0xb1
	s_cselect_b32 s36, s36, 0xb0
	s_mul_i32 s34, s36, s34
	s_add_i32 s34, s34, s35
	s_mul_hi_i32 s35, s34, 0x2e8ba2e9
	s_lshr_b32 s36, s35, 31
	s_ashr_i32 s35, s35, 6
	s_add_i32 s35, s35, s36
	s_lshl_b32 s36, s35, 3
	s_mulk_i32 s35, 0x160
	s_sub_i32 s34, s34, s35
	s_bfe_u32 s35, s34, 0x3001c
	s_add_i32 s35, s34, s35
	s_and_b32 s37, s35, 0xfff8
	s_sub_i32 s34, s34, s37
	s_sext_i32_i16 s34, s34
	s_sext_i32_i16 s35, s35
	s_add_i32 s36, s36, s34
	s_lshl_b32 s35, s35, 5
	s_lshl_b32 s34, s36, 8
	s_and_b32 s36, s35, 0xffffff00
	s_ashr_i32 s35, s34, 31
	s_ashr_i32 s37, s36, 31
	s_lshl_b64 s[18:19], s[34:35], 12
	s_lshl_b64 s[16:17], s[36:37], 12
	s_add_u32 s20, s22, s16
	s_addc_u32 s21, s23, s17
	v_readlane_b32 s100, v253, 54
	v_readlane_b32 s101, v253, 55
	s_add_u32 s100, s100, s18
	s_addc_u32 s101, s101, s19
	v_lshl_add_u64 v[242:243], s[20:21], 0, v[132:133]
	s_add_i32 m0, s26, 0x10000
	s_nop 0
	global_load_lds_dwordx4 v[242:243], off
	v_lshl_add_u64 v[242:243], s[20:21], 0, v[130:131]
	s_add_i32 m0, s26, 0x12000
	s_nop 0
	global_load_lds_dwordx4 v[242:243], off
	v_lshl_add_u64 v[242:243], s[100:101], 0, v[132:133]
	s_mov_b32 m0, s26
	s_nop 0
	global_load_lds_dwordx4 v[242:243], off
	v_lshl_add_u64 v[242:243], s[100:101], 0, v[130:131]
	s_add_i32 m0, s26, 0x2000
	s_nop 0
	global_load_lds_dwordx4 v[242:243], off
	s_add_u32 s36, s20, 0x80000
	s_addc_u32 s37, s21, 0
	v_lshl_add_u64 v[242:243], s[36:37], 0, v[132:133]
	s_add_i32 m0, s26, 0x14000
	s_nop 0
	global_load_lds_dwordx4 v[242:243], off
	v_lshl_add_u64 v[242:243], s[36:37], 0, v[130:131]
	s_add_i32 m0, s26, 0x16000
	s_nop 0
	global_load_lds_dwordx4 v[242:243], off
	s_add_u32 s36, s100, 0x80000
	s_addc_u32 s37, s101, 0
	v_lshl_add_u64 v[242:243], s[36:37], 0, v[132:133]
	s_add_i32 m0, s26, 0x4000
	s_nop 0
	global_load_lds_dwordx4 v[242:243], off
	v_lshl_add_u64 v[242:243], s[36:37], 0, v[130:131]
	s_add_i32 m0, s26, 0x6000
	s_nop 0
	global_load_lds_dwordx4 v[242:243], off
.Lpf_skip:
	v_lshrrev_b32_e32 v0, 1, v0
	v_and_b32_e32 v0, 24, v0
	v_lshl_add_u64 v[134:135], s[0:1], 0, v[0:1]
	s_or_b32 s10, s12, s25
	s_ashr_i32 s10, s10, 1
	s_movk_i32 s15, 0x2c00
	s_ashr_i32 s11, s10, 31
	s_lshl_b64 s[10:11], s[10:11], 1
	s_waitcnt vmcnt(14)
	v_mov_b32_e32 v138, v162
	v_mov_b32_e32 v139, v166
	v_mov_b32_e32 v166, v163
	v_mov_b32_e32 v162, v164
	v_mov_b32_e32 v163, v168
	v_mov_b32_e32 v168, v165
	v_pk_add_f32 v[138:139], v[138:139], v[166:167]
	v_pk_add_f32 v[162:163], v[162:163], v[168:169]
	s_nop 0
	v_pk_add_f32 v[138:139], v[138:139], v[162:163]
	s_nop 0
	v_add_f32_e32 v0, v138, v139
	v_fmamk_f32 v0, v0, 0x3a000000, v249
	v_cmp_gt_f32_e32 vcc, s14, v0
	v_mul_f32_e32 v137, 0x4b800000, v0
	v_mad_i64_i32 v[138:139], s[12:13], v136, s15, v[134:135]
	v_cndmask_b32_e32 v0, v0, v137, vcc
	v_rsq_f32_e32 v0, v0
	s_nop 0
	v_mul_f32_e32 v137, 0x45800000, v0
	v_cndmask_b32_e32 v0, v0, v137, vcc
	v_pk_mul_f32 v[122:123], v[122:123], v[0:1] op_sel_hi:[1,0]
	v_pk_mul_f32 v[124:125], v[124:125], v[0:1] op_sel_hi:[1,0]
	v_mul_f32_e32 v137, 0xbfb8aa3b, v122
	v_exp_f32_e32 v137, v137
	v_pk_mul_f32 v[126:127], v[126:127], v[0:1] op_sel_hi:[1,0]
	v_pk_mul_f32 v[118:119], v[118:119], v[0:1] op_sel_hi:[1,0]
	v_pk_mul_f32 v[128:129], v[128:129], v[0:1] op_sel_hi:[1,0]
	v_add_f32_e32 v137, 1.0, v137
	v_rcp_f32_e32 v142, v137
	v_mul_f32_e32 v137, 0xbfb8aa3b, v123
	v_exp_f32_e32 v137, v137
	v_pk_mul_f32 v[120:121], v[120:121], v[0:1] op_sel_hi:[1,0]
	v_pk_mul_f32 v[116:117], v[116:117], v[0:1] op_sel_hi:[1,0]
	v_pk_mul_f32 v[114:115], v[114:115], v[0:1] op_sel_hi:[1,0]
	v_add_f32_e32 v137, 1.0, v137
	v_rcp_f32_e32 v143, v137
	v_mul_f32_e32 v0, 0xbfb8aa3b, v118
	v_exp_f32_e32 v0, v0
	v_pk_mul_f32 v[122:123], v[122:123], v[142:143]
	s_nop 0
	v_pk_mul_f32 v[122:123], v[126:127], v[122:123]
	v_mul_f32_e32 v126, 0xbfb8aa3b, v124
	v_mul_f32_e32 v127, 0xbfb8aa3b, v125
	v_exp_f32_e32 v126, v126
	v_exp_f32_e32 v127, v127
	v_cvt_pk_bf16_f32 v122, v122, v123
	v_add_f32_e32 v0, 1.0, v0
	v_add_f32_e32 v126, 1.0, v126
	v_add_f32_e32 v127, 1.0, v127
	v_rcp_f32_e32 v126, v126
	v_rcp_f32_e32 v127, v127
	s_nop 0
	v_pk_mul_f32 v[124:125], v[124:125], v[126:127]
	s_nop 0
	v_pk_mul_f32 v[124:125], v[128:129], v[124:125]
	v_lshl_add_u64 v[126:127], v[138:139], 0, s[10:11]
	v_cvt_pk_bf16_f32 v123, v124, v125
	global_store_dwordx2 v[126:127], v[122:123], off
	v_rcp_f32_e32 v122, v0
	v_mul_f32_e32 v0, 0xbfb8aa3b, v119
	v_exp_f32_e32 v0, v0
	s_nop 0
	v_add_f32_e32 v0, 1.0, v0
	v_rcp_f32_e32 v123, v0
	v_mul_f32_e32 v0, 0xbfb8aa3b, v120
	v_exp_f32_e32 v0, v0
	v_pk_mul_f32 v[118:119], v[118:119], v[122:123]
	s_nop 0
	v_pk_mul_f32 v[114:115], v[114:115], v[118:119]
	v_add_f32_e32 v0, 1.0, v0
	v_rcp_f32_e32 v118, v0
	v_mul_f32_e32 v0, 0xbfb8aa3b, v121
	v_exp_f32_e32 v0, v0
	v_cvt_pk_bf16_f32 v114, v114, v115
	v_add_f32_e32 v0, 1.0, v0
	v_rcp_f32_e32 v119, v0
	s_nop 0
	v_pk_mul_f32 v[118:119], v[120:121], v[118:119]
	s_nop 0
	v_pk_mul_f32 v[116:117], v[116:117], v[118:119]
	s_nop 0
	v_cvt_pk_bf16_f32 v115, v116, v117
	global_store_dwordx2 v[126:127], v[114:115], off offset:128
	v_or_b32_e32 v122, 16, v136
	v_ashrrev_i32_e32 v123, 31, v122
	v_lshlrev_b64 v[114:115], 5, v[122:123]
	v_lshl_add_u64 v[118:119], s[4:5], 0, v[114:115]
	s_nop 0
	s_waitcnt vmcnt(12)
; DI float sigmoidf_(float x) { return frcp(1.f + __expf(-x)); }
; DI void st_bf16x4(bf16_t* p, f32x4 v) { u32x2 o; o.x = pk2e(v[0], v[1]); o.y = pk2e(v[2], v[3]); *(u32x2*)p = o; }
;   DI float operator()(int row, int colbase, int fq, f32x4 v0, f32x4 v1) const { one(row, colbase + 4 * fq, v0); one(row, colbase + 16 + 4 * fq, v1); return 0.f; }
;   DI float operator()(int row, int colbase, int fq, f32x4 v0, f32x4 v1) const { one(row, colbase + 4 * fq, v0); one(row, colbase + 16 + 4 * fq, v1); return 0.f; }
;   DI float operator()(int row, int colbase, int fq, f32x4 v0, f32x4 v1) const { one(row, colbase + 4 * fq, v0); one(row, colbase + 16 + 4 * fq, v1); return 0.f; }
;   DI float operator()(int row, int colbase, int fq, f32x4 v0, f32x4 v1) const { one(row, colbase + 4 * fq, v0); one(row, colbase + 16 + 4 * fq, v1); return 0.f; }
;     ...
;     for (int ai = 0; ai < 2; ++ai)
; #pragma unroll
;       for (int m = 0; m < 4; ++m) {
;         const int row = brow + ai * HALF + wr * 64 + m * 16 + fr_e;
;         const float rsc = epi.rowscale(row);
;         float ssq = 0.f;
; #pragma unroll
;         for (int bj = 0; bj < 2; ++bj)
;           ssq += epi(row, bcol + bj * HALF + wc * 32, fq_e, acc[ai][bj][m][0] * rsc, acc[ai][bj][m][1] * rsc);
;         rowss[ai][m] = ssq;
;   DI float rowscale(int row) const { const f32x4 a = *(const f32x4*)(ssp_in + (size_t)row * 8), b = *(const f32x4*)(ssp_in + (size_t)row * 8 + 4);
;     return rsqrtf((((a[0] + a[1]) + (a[2] + a[3])) + ((b[0] + b[1]) + (b[2] + b[3]))) * (1.f / D_) + EPS_); }
;   DI float operator()(int row, int colbase, int fq, f32x4 v0, f32x4 v1) const {
;     f32x4 r;
; #pragma unroll
;     for (int e = 0; e < 4; ++e) r[e] = v0[e] * sigmoidf_(v0[e]) * v1[e];
;     st_bf16x4(hid + (size_t)row * FFN_ + (colbase >> 1) + 4 * fq, r); return 0.f;
	v_mov_b32_e32 v124, v170
	v_mov_b32_e32 v125, v174
	v_mov_b32_e32 v174, v171
	v_pk_add_f32 v[170:171], v[124:125], v[174:175]
	v_mov_b32_e32 v174, v172
	v_mov_b32_e32 v175, v176
	v_mov_b32_e32 v176, v173
	v_pk_add_f32 v[172:173], v[174:175], v[176:177]
	s_nop 0
	v_pk_add_f32 v[170:171], v[170:171], v[172:173]
	s_nop 0
	v_add_f32_e32 v0, v170, v171
	v_fmamk_f32 v0, v0, 0x3a000000, v249
	v_cmp_gt_f32_e32 vcc, s14, v0
	v_mul_f32_e32 v114, 0x4b800000, v0
	s_nop 0
	v_cndmask_b32_e32 v0, v0, v114, vcc
	v_rsq_f32_e32 v0, v0
	s_nop 0
	v_mul_f32_e32 v114, 0x45800000, v0
	v_cndmask_b32_e32 v0, v0, v114, vcc
	v_pk_mul_f32 v[106:107], v[106:107], v[0:1] op_sel_hi:[1,0]
	v_pk_mul_f32 v[108:109], v[108:109], v[0:1] op_sel_hi:[1,0]
	v_mul_f32_e32 v116, 0xbfb8aa3b, v106
	v_mul_f32_e32 v117, 0xbfb8aa3b, v107
	v_exp_f32_e32 v116, v116
	v_exp_f32_e32 v117, v117
	v_pk_mul_f32 v[110:111], v[110:111], v[0:1] op_sel_hi:[1,0]
	v_pk_mul_f32 v[102:103], v[102:103], v[0:1] op_sel_hi:[1,0]
	v_add_f32_e32 v116, 1.0, v116
	v_add_f32_e32 v117, 1.0, v117
	v_rcp_f32_e32 v116, v116
	v_rcp_f32_e32 v117, v117
	v_pk_mul_f32 v[112:113], v[112:113], v[0:1] op_sel_hi:[1,0]
	v_pk_mul_f32 v[104:105], v[104:105], v[0:1] op_sel_hi:[1,0]
	v_pk_mul_f32 v[100:101], v[100:101], v[0:1] op_sel_hi:[1,0]
	v_pk_mul_f32 v[106:107], v[106:107], v[116:117]
	v_pk_mul_f32 v[98:99], v[98:99], v[0:1] op_sel_hi:[1,0]
	v_pk_mul_f32 v[110:111], v[110:111], v[106:107]
	v_mul_f32_e32 v106, 0xbfb8aa3b, v108
	v_mul_f32_e32 v107, 0xbfb8aa3b, v109
	v_exp_f32_e32 v106, v106
	v_exp_f32_e32 v107, v107
	v_mul_f32_e32 v0, 0xbfb8aa3b, v102
	v_exp_f32_e32 v0, v0
	v_add_f32_e32 v106, 1.0, v106
	v_add_f32_e32 v107, 1.0, v107
	v_rcp_f32_e32 v106, v106
	v_rcp_f32_e32 v107, v107
	v_add_f32_e32 v0, 1.0, v0
	v_cvt_pk_bf16_f32 v110, v110, v111
	v_mad_i64_i32 v[114:115], s[12:13], v122, s15, v[134:135]
	v_pk_mul_f32 v[106:107], v[108:109], v[106:107]
	s_nop 0
	v_pk_mul_f32 v[108:109], v[112:113], v[106:107]
	v_lshl_add_u64 v[106:107], v[114:115], 0, s[10:11]
	v_cvt_pk_bf16_f32 v111, v108, v109
	v_rcp_f32_e32 v108, v0
	v_mul_f32_e32 v0, 0xbfb8aa3b, v103
	v_exp_f32_e32 v0, v0
	global_store_dwordx2 v[106:107], v[110:111], off
	v_add_f32_e32 v0, 1.0, v0
	v_rcp_f32_e32 v109, v0
	v_mul_f32_e32 v0, 0xbfb8aa3b, v104
	v_exp_f32_e32 v0, v0
	v_pk_mul_f32 v[102:103], v[102:103], v[108:109]
	s_nop 0
	v_pk_mul_f32 v[98:99], v[98:99], v[102:103]
	v_add_f32_e32 v0, 1.0, v0
	v_rcp_f32_e32 v102, v0
	v_mul_f32_e32 v0, 0xbfb8aa3b, v105
	v_exp_f32_e32 v0, v0
	v_cvt_pk_bf16_f32 v98, v98, v99
	v_add_f32_e32 v0, 1.0, v0
	v_rcp_f32_e32 v103, v0
	s_nop 0
	v_pk_mul_f32 v[102:103], v[104:105], v[102:103]
	s_nop 0
	v_pk_mul_f32 v[100:101], v[100:101], v[102:103]
	s_nop 0
	v_cvt_pk_bf16_f32 v99, v100, v101
	global_store_dwordx2 v[106:107], v[98:99], off offset:128
	v_or_b32_e32 v106, 32, v136
	v_ashrrev_i32_e32 v107, 31, v106
	v_lshlrev_b64 v[98:99], 5, v[106:107]
	v_lshl_add_u64 v[102:103], s[4:5], 0, v[98:99]
	s_nop 0
	s_waitcnt vmcnt(10)
	v_mov_b32_e32 v108, v178
	v_mov_b32_e32 v109, v182
	v_mov_b32_e32 v182, v179
	v_pk_add_f32 v[178:179], v[108:109], v[182:183]
	v_mov_b32_e32 v182, v180
	v_mov_b32_e32 v183, v184
	v_mov_b32_e32 v184, v181
	v_pk_add_f32 v[180:181], v[182:183], v[184:185]
	s_nop 0
	v_pk_add_f32 v[178:179], v[178:179], v[180:181]
	s_nop 0
	v_add_f32_e32 v0, v178, v179
	v_fmamk_f32 v0, v0, 0x3a000000, v249
	v_cmp_gt_f32_e32 vcc, s14, v0
	v_mul_f32_e32 v98, 0x4b800000, v0
	s_nop 0
	v_cndmask_b32_e32 v0, v0, v98, vcc
	v_rsq_f32_e32 v0, v0
	s_nop 0
	v_mul_f32_e32 v98, 0x45800000, v0
	v_cndmask_b32_e32 v0, v0, v98, vcc
	v_pk_mul_f32 v[90:91], v[90:91], v[0:1] op_sel_hi:[1,0]
	v_pk_mul_f32 v[92:93], v[92:93], v[0:1] op_sel_hi:[1,0]
	v_mul_f32_e32 v100, 0xbfb8aa3b, v90
	v_mul_f32_e32 v101, 0xbfb8aa3b, v91
	v_exp_f32_e32 v100, v100
	v_exp_f32_e32 v101, v101
	v_pk_mul_f32 v[94:95], v[94:95], v[0:1] op_sel_hi:[1,0]
	v_pk_mul_f32 v[86:87], v[86:87], v[0:1] op_sel_hi:[1,0]
	v_add_f32_e32 v100, 1.0, v100
	v_add_f32_e32 v101, 1.0, v101
	v_rcp_f32_e32 v100, v100
	v_rcp_f32_e32 v101, v101
	v_pk_mul_f32 v[96:97], v[96:97], v[0:1] op_sel_hi:[1,0]
	v_pk_mul_f32 v[88:89], v[88:89], v[0:1] op_sel_hi:[1,0]
	v_pk_mul_f32 v[84:85], v[84:85], v[0:1] op_sel_hi:[1,0]
	v_pk_mul_f32 v[90:91], v[90:91], v[100:101]
	v_pk_mul_f32 v[82:83], v[82:83], v[0:1] op_sel_hi:[1,0]
	v_pk_mul_f32 v[94:95], v[94:95], v[90:91]
	v_mul_f32_e32 v90, 0xbfb8aa3b, v92
	v_mul_f32_e32 v91, 0xbfb8aa3b, v93
	v_exp_f32_e32 v90, v90
	v_exp_f32_e32 v91, v91
	v_mul_f32_e32 v0, 0xbfb8aa3b, v86
	v_exp_f32_e32 v0, v0
	v_add_f32_e32 v90, 1.0, v90
	v_add_f32_e32 v91, 1.0, v91
	v_rcp_f32_e32 v90, v90
	v_rcp_f32_e32 v91, v91
	v_add_f32_e32 v0, 1.0, v0
	v_cvt_pk_bf16_f32 v94, v94, v95
	v_mad_i64_i32 v[98:99], s[12:13], v106, s15, v[134:135]
	v_pk_mul_f32 v[90:91], v[92:93], v[90:91]
	s_nop 0
	v_pk_mul_f32 v[92:93], v[96:97], v[90:91]
	v_lshl_add_u64 v[90:91], v[98:99], 0, s[10:11]
	v_cvt_pk_bf16_f32 v95, v92, v93
	v_rcp_f32_e32 v92, v0
	v_mul_f32_e32 v0, 0xbfb8aa3b, v87
	v_exp_f32_e32 v0, v0
	global_store_dwordx2 v[90:91], v[94:95], off
	v_add_f32_e32 v0, 1.0, v0
	v_rcp_f32_e32 v93, v0
	v_mul_f32_e32 v0, 0xbfb8aa3b, v88
	v_exp_f32_e32 v0, v0
	v_pk_mul_f32 v[86:87], v[86:87], v[92:93]
	s_nop 0
	v_pk_mul_f32 v[82:83], v[82:83], v[86:87]
	v_add_f32_e32 v0, 1.0, v0
	v_rcp_f32_e32 v86, v0
	v_mul_f32_e32 v0, 0xbfb8aa3b, v89
	v_exp_f32_e32 v0, v0
	v_cvt_pk_bf16_f32 v82, v82, v83
	v_add_f32_e32 v0, 1.0, v0
	v_rcp_f32_e32 v87, v0
	s_nop 0
	v_pk_mul_f32 v[86:87], v[88:89], v[86:87]
	s_nop 0
	v_pk_mul_f32 v[84:85], v[84:85], v[86:87]
	s_nop 0
	v_cvt_pk_bf16_f32 v83, v84, v85
	global_store_dwordx2 v[90:91], v[82:83], off offset:128
	v_or_b32_e32 v90, 48, v136
	v_ashrrev_i32_e32 v91, 31, v90
	v_lshlrev_b64 v[82:83], 5, v[90:91]
	v_lshl_add_u64 v[86:87], s[4:5], 0, v[82:83]
	s_nop 0
	s_waitcnt vmcnt(8)
; DI float sigmoidf_(float x) { return frcp(1.f + __expf(-x)); }
; DI void st_bf16x4(bf16_t* p, f32x4 v) { u32x2 o; o.x = pk2e(v[0], v[1]); o.y = pk2e(v[2], v[3]); *(u32x2*)p = o; }
;   DI float operator()(int row, int colbase, int fq, f32x4 v0, f32x4 v1) const { one(row, colbase + 4 * fq, v0); one(row, colbase + 16 + 4 * fq, v1); return 0.f; }
;   DI float operator()(int row, int colbase, int fq, f32x4 v0, f32x4 v1) const { one(row, colbase + 4 * fq, v0); one(row, colbase + 16 + 4 * fq, v1); return 0.f; }
;   DI float operator()(int row, int colbase, int fq, f32x4 v0, f32x4 v1) const { one(row, colbase + 4 * fq, v0); one(row, colbase + 16 + 4 * fq, v1); return 0.f; }
;   DI float operator()(int row, int colbase, int fq, f32x4 v0, f32x4 v1) const { one(row, colbase + 4 * fq, v0); one(row, colbase + 16 + 4 * fq, v1); return 0.f; }
;     ...
;     for (int ai = 0; ai < 2; ++ai)
; #pragma unroll
;       for (int m = 0; m < 4; ++m) {
;         const int row = brow + ai * HALF + wr * 64 + m * 16 + fr_e;
;         const float rsc = epi.rowscale(row);
;         float ssq = 0.f;
; #pragma unroll
;         for (int bj = 0; bj < 2; ++bj)
;           ssq += epi(row, bcol + bj * HALF + wc * 32, fq_e, acc[ai][bj][m][0] * rsc, acc[ai][bj][m][1] * rsc);
;         rowss[ai][m] = ssq;
;   DI float rowscale(int row) const { const f32x4 a = *(const f32x4*)(ssp_in + (size_t)row * 8), b = *(const f32x4*)(ssp_in + (size_t)row * 8 + 4);
;     return rsqrtf((((a[0] + a[1]) + (a[2] + a[3])) + ((b[0] + b[1]) + (b[2] + b[3]))) * (1.f / D_) + EPS_); }
;   DI float operator()(int row, int colbase, int fq, f32x4 v0, f32x4 v1) const {
;     f32x4 r;
; #pragma unroll
;     for (int e = 0; e < 4; ++e) r[e] = v0[e] * sigmoidf_(v0[e]) * v1[e];
;     st_bf16x4(hid + (size_t)row * FFN_ + (colbase >> 1) + 4 * fq, r); return 0.f;
	v_mov_b32_e32 v92, v200
	v_mov_b32_e32 v93, v204
	v_mov_b32_e32 v204, v201
	v_pk_add_f32 v[200:201], v[92:93], v[204:205]
	v_mov_b32_e32 v204, v202
	v_mov_b32_e32 v205, v206
	v_mov_b32_e32 v206, v203
	v_pk_add_f32 v[202:203], v[204:205], v[206:207]
	s_nop 0
	v_pk_add_f32 v[200:201], v[200:201], v[202:203]
	s_nop 0
	v_add_f32_e32 v0, v200, v201
	v_fmamk_f32 v0, v0, 0x3a000000, v249
	v_cmp_gt_f32_e32 vcc, s14, v0
	v_mul_f32_e32 v82, 0x4b800000, v0
	s_nop 0
	v_cndmask_b32_e32 v0, v0, v82, vcc
	v_rsq_f32_e32 v0, v0
	s_nop 0
	v_mul_f32_e32 v82, 0x45800000, v0
	v_cndmask_b32_e32 v0, v0, v82, vcc
	v_pk_mul_f32 v[74:75], v[74:75], v[0:1] op_sel_hi:[1,0]
	v_pk_mul_f32 v[76:77], v[76:77], v[0:1] op_sel_hi:[1,0]
	v_mul_f32_e32 v84, 0xbfb8aa3b, v74
	v_mul_f32_e32 v85, 0xbfb8aa3b, v75
	v_exp_f32_e32 v84, v84
	v_exp_f32_e32 v85, v85
	v_pk_mul_f32 v[78:79], v[78:79], v[0:1] op_sel_hi:[1,0]
	v_pk_mul_f32 v[70:71], v[70:71], v[0:1] op_sel_hi:[1,0]
	v_add_f32_e32 v84, 1.0, v84
	v_add_f32_e32 v85, 1.0, v85
	v_rcp_f32_e32 v84, v84
	v_rcp_f32_e32 v85, v85
	v_pk_mul_f32 v[80:81], v[80:81], v[0:1] op_sel_hi:[1,0]
	v_pk_mul_f32 v[72:73], v[72:73], v[0:1] op_sel_hi:[1,0]
	v_pk_mul_f32 v[68:69], v[68:69], v[0:1] op_sel_hi:[1,0]
	v_pk_mul_f32 v[74:75], v[74:75], v[84:85]
	v_pk_mul_f32 v[66:67], v[66:67], v[0:1] op_sel_hi:[1,0]
	v_pk_mul_f32 v[78:79], v[78:79], v[74:75]
	v_mul_f32_e32 v74, 0xbfb8aa3b, v76
	v_mul_f32_e32 v75, 0xbfb8aa3b, v77
	v_exp_f32_e32 v74, v74
	v_exp_f32_e32 v75, v75
	v_mul_f32_e32 v0, 0xbfb8aa3b, v70
	v_exp_f32_e32 v0, v0
	v_add_f32_e32 v74, 1.0, v74
	v_add_f32_e32 v75, 1.0, v75
	v_rcp_f32_e32 v74, v74
	v_rcp_f32_e32 v75, v75
	v_add_f32_e32 v0, 1.0, v0
	v_cvt_pk_bf16_f32 v78, v78, v79
	v_mad_i64_i32 v[82:83], s[12:13], v90, s15, v[134:135]
	v_pk_mul_f32 v[74:75], v[76:77], v[74:75]
	s_nop 0
	v_pk_mul_f32 v[76:77], v[80:81], v[74:75]
	v_lshl_add_u64 v[74:75], v[82:83], 0, s[10:11]
	v_cvt_pk_bf16_f32 v79, v76, v77
	v_rcp_f32_e32 v76, v0
	v_mul_f32_e32 v0, 0xbfb8aa3b, v71
	v_exp_f32_e32 v0, v0
	global_store_dwordx2 v[74:75], v[78:79], off
	v_add_f32_e32 v0, 1.0, v0
	v_rcp_f32_e32 v77, v0
	v_mul_f32_e32 v0, 0xbfb8aa3b, v72
	v_exp_f32_e32 v0, v0
	v_pk_mul_f32 v[70:71], v[70:71], v[76:77]
	s_nop 0
	v_pk_mul_f32 v[66:67], v[66:67], v[70:71]
	v_add_f32_e32 v0, 1.0, v0
	v_rcp_f32_e32 v70, v0
	v_mul_f32_e32 v0, 0xbfb8aa3b, v73
	v_exp_f32_e32 v0, v0
	v_cvt_pk_bf16_f32 v66, v66, v67
	v_add_f32_e32 v0, 1.0, v0
	v_rcp_f32_e32 v71, v0
	s_nop 0
	v_pk_mul_f32 v[70:71], v[72:73], v[70:71]
	s_nop 0
	v_pk_mul_f32 v[68:69], v[68:69], v[70:71]
	s_nop 0
	v_cvt_pk_bf16_f32 v67, v68, v69
	global_store_dwordx2 v[74:75], v[66:67], off offset:128
	v_add_u32_e32 v74, 0x80, v136
	v_ashrrev_i32_e32 v75, 31, v74
	v_lshlrev_b64 v[66:67], 5, v[74:75]
	v_lshl_add_u64 v[70:71], s[4:5], 0, v[66:67]
	s_nop 0
	s_waitcnt vmcnt(6)
	v_mov_b32_e32 v76, v208
	v_mov_b32_e32 v77, v212
	v_mov_b32_e32 v212, v209
	v_pk_add_f32 v[208:209], v[76:77], v[212:213]
	v_mov_b32_e32 v212, v210
	v_mov_b32_e32 v213, v214
	v_mov_b32_e32 v214, v211
	v_pk_add_f32 v[210:211], v[212:213], v[214:215]
	s_nop 0
	v_pk_add_f32 v[208:209], v[208:209], v[210:211]
	s_nop 0
	v_add_f32_e32 v0, v208, v209
	v_fmamk_f32 v0, v0, 0x3a000000, v249
	v_cmp_gt_f32_e32 vcc, s14, v0
	v_mul_f32_e32 v66, 0x4b800000, v0
	s_nop 0
	v_cndmask_b32_e32 v0, v0, v66, vcc
	v_rsq_f32_e32 v0, v0
	s_nop 0
	v_mul_f32_e32 v66, 0x45800000, v0
	v_cndmask_b32_e32 v0, v0, v66, vcc
	v_pk_mul_f32 v[58:59], v[58:59], v[0:1] op_sel_hi:[1,0]
	v_pk_mul_f32 v[60:61], v[60:61], v[0:1] op_sel_hi:[1,0]
	v_mul_f32_e32 v68, 0xbfb8aa3b, v58
	v_mul_f32_e32 v69, 0xbfb8aa3b, v59
	v_exp_f32_e32 v68, v68
	v_exp_f32_e32 v69, v69
	v_pk_mul_f32 v[62:63], v[62:63], v[0:1] op_sel_hi:[1,0]
	v_pk_mul_f32 v[54:55], v[54:55], v[0:1] op_sel_hi:[1,0]
	v_add_f32_e32 v68, 1.0, v68
	v_add_f32_e32 v69, 1.0, v69
	v_rcp_f32_e32 v68, v68
	v_rcp_f32_e32 v69, v69
	v_pk_mul_f32 v[64:65], v[64:65], v[0:1] op_sel_hi:[1,0]
	v_pk_mul_f32 v[56:57], v[56:57], v[0:1] op_sel_hi:[1,0]
	v_pk_mul_f32 v[52:53], v[52:53], v[0:1] op_sel_hi:[1,0]
	v_pk_mul_f32 v[58:59], v[58:59], v[68:69]
	v_pk_mul_f32 v[50:51], v[50:51], v[0:1] op_sel_hi:[1,0]
	v_pk_mul_f32 v[62:63], v[62:63], v[58:59]
	v_mul_f32_e32 v58, 0xbfb8aa3b, v60
	v_mul_f32_e32 v59, 0xbfb8aa3b, v61
	v_exp_f32_e32 v58, v58
	v_exp_f32_e32 v59, v59
	v_mul_f32_e32 v0, 0xbfb8aa3b, v54
	v_exp_f32_e32 v0, v0
	v_add_f32_e32 v58, 1.0, v58
	v_add_f32_e32 v59, 1.0, v59
	v_rcp_f32_e32 v58, v58
	v_rcp_f32_e32 v59, v59
	v_add_f32_e32 v0, 1.0, v0
	v_cvt_pk_bf16_f32 v62, v62, v63
	v_mad_i64_i32 v[66:67], s[12:13], v74, s15, v[134:135]
	v_pk_mul_f32 v[58:59], v[60:61], v[58:59]
	s_nop 0
	v_pk_mul_f32 v[60:61], v[64:65], v[58:59]
	v_lshl_add_u64 v[58:59], v[66:67], 0, s[10:11]
	v_cvt_pk_bf16_f32 v63, v60, v61
	v_rcp_f32_e32 v60, v0
	v_mul_f32_e32 v0, 0xbfb8aa3b, v55
	v_exp_f32_e32 v0, v0
	global_store_dwordx2 v[58:59], v[62:63], off
	v_add_f32_e32 v0, 1.0, v0
	v_rcp_f32_e32 v61, v0
	v_mul_f32_e32 v0, 0xbfb8aa3b, v56
	v_exp_f32_e32 v0, v0
	v_pk_mul_f32 v[54:55], v[54:55], v[60:61]
	s_nop 0
	v_pk_mul_f32 v[50:51], v[50:51], v[54:55]
	v_add_f32_e32 v0, 1.0, v0
	v_rcp_f32_e32 v54, v0
	v_mul_f32_e32 v0, 0xbfb8aa3b, v57
	v_exp_f32_e32 v0, v0
	v_cvt_pk_bf16_f32 v50, v50, v51
	v_add_f32_e32 v0, 1.0, v0
	v_rcp_f32_e32 v55, v0
	s_nop 0
	v_pk_mul_f32 v[54:55], v[56:57], v[54:55]
	s_nop 0
	v_pk_mul_f32 v[52:53], v[52:53], v[54:55]
	s_nop 0
	v_cvt_pk_bf16_f32 v51, v52, v53
	global_store_dwordx2 v[58:59], v[50:51], off offset:128
	v_add_u32_e32 v58, 0x90, v136
	v_ashrrev_i32_e32 v59, 31, v58
	v_lshlrev_b64 v[50:51], 5, v[58:59]
	v_lshl_add_u64 v[54:55], s[4:5], 0, v[50:51]
	s_nop 0
	s_waitcnt vmcnt(4)
; DI float sigmoidf_(float x) { return frcp(1.f + __expf(-x)); }
; DI void st_bf16x4(bf16_t* p, f32x4 v) { u32x2 o; o.x = pk2e(v[0], v[1]); o.y = pk2e(v[2], v[3]); *(u32x2*)p = o; }
;   DI float operator()(int row, int colbase, int fq, f32x4 v0, f32x4 v1) const { one(row, colbase + 4 * fq, v0); one(row, colbase + 16 + 4 * fq, v1); return 0.f; }
;   DI float operator()(int row, int colbase, int fq, f32x4 v0, f32x4 v1) const { one(row, colbase + 4 * fq, v0); one(row, colbase + 16 + 4 * fq, v1); return 0.f; }
;   DI float operator()(int row, int colbase, int fq, f32x4 v0, f32x4 v1) const { one(row, colbase + 4 * fq, v0); one(row, colbase + 16 + 4 * fq, v1); return 0.f; }
;   DI float operator()(int row, int colbase, int fq, f32x4 v0, f32x4 v1) const { one(row, colbase + 4 * fq, v0); one(row, colbase + 16 + 4 * fq, v1); return 0.f; }
;     ...
;     for (int ai = 0; ai < 2; ++ai)
; #pragma unroll
;       for (int m = 0; m < 4; ++m) {
;         const int row = brow + ai * HALF + wr * 64 + m * 16 + fr_e;
;         const float rsc = epi.rowscale(row);
;         float ssq = 0.f;
; #pragma unroll
;         for (int bj = 0; bj < 2; ++bj)
;           ssq += epi(row, bcol + bj * HALF + wc * 32, fq_e, acc[ai][bj][m][0] * rsc, acc[ai][bj][m][1] * rsc);
;         rowss[ai][m] = ssq;
;   DI float rowscale(int row) const { const f32x4 a = *(const f32x4*)(ssp_in + (size_t)row * 8), b = *(const f32x4*)(ssp_in + (size_t)row * 8 + 4);
;     return rsqrtf((((a[0] + a[1]) + (a[2] + a[3])) + ((b[0] + b[1]) + (b[2] + b[3]))) * (1.f / D_) + EPS_); }
;   DI float operator()(int row, int colbase, int fq, f32x4 v0, f32x4 v1) const {
;     f32x4 r;
; #pragma unroll
;     for (int e = 0; e < 4; ++e) r[e] = v0[e] * sigmoidf_(v0[e]) * v1[e];
;     st_bf16x4(hid + (size_t)row * FFN_ + (colbase >> 1) + 4 * fq, r); return 0.f;
	v_mov_b32_e32 v60, v216
	v_mov_b32_e32 v61, v220
	v_mov_b32_e32 v220, v217
	v_pk_add_f32 v[216:217], v[60:61], v[220:221]
	v_mov_b32_e32 v220, v218
	v_mov_b32_e32 v221, v222
	v_mov_b32_e32 v222, v219
	v_pk_add_f32 v[218:219], v[220:221], v[222:223]
	s_nop 0
	v_pk_add_f32 v[216:217], v[216:217], v[218:219]
	s_nop 0
	v_add_f32_e32 v0, v216, v217
	v_fmamk_f32 v0, v0, 0x3a000000, v249
	v_cmp_gt_f32_e32 vcc, s14, v0
	v_mul_f32_e32 v50, 0x4b800000, v0
	s_nop 0
	v_cndmask_b32_e32 v0, v0, v50, vcc
	v_rsq_f32_e32 v0, v0
	s_nop 0
	v_mul_f32_e32 v50, 0x45800000, v0
	v_cndmask_b32_e32 v0, v0, v50, vcc
	v_pk_mul_f32 v[42:43], v[42:43], v[0:1] op_sel_hi:[1,0]
	v_pk_mul_f32 v[44:45], v[44:45], v[0:1] op_sel_hi:[1,0]
	v_mul_f32_e32 v52, 0xbfb8aa3b, v42
	v_mul_f32_e32 v53, 0xbfb8aa3b, v43
	v_exp_f32_e32 v52, v52
	v_exp_f32_e32 v53, v53
	v_pk_mul_f32 v[46:47], v[46:47], v[0:1] op_sel_hi:[1,0]
	v_pk_mul_f32 v[38:39], v[38:39], v[0:1] op_sel_hi:[1,0]
	v_add_f32_e32 v52, 1.0, v52
	v_add_f32_e32 v53, 1.0, v53
	v_rcp_f32_e32 v52, v52
	v_rcp_f32_e32 v53, v53
	v_pk_mul_f32 v[48:49], v[48:49], v[0:1] op_sel_hi:[1,0]
	v_pk_mul_f32 v[40:41], v[40:41], v[0:1] op_sel_hi:[1,0]
	v_pk_mul_f32 v[36:37], v[36:37], v[0:1] op_sel_hi:[1,0]
	v_pk_mul_f32 v[42:43], v[42:43], v[52:53]
	v_pk_mul_f32 v[34:35], v[34:35], v[0:1] op_sel_hi:[1,0]
	v_pk_mul_f32 v[46:47], v[46:47], v[42:43]
	v_mul_f32_e32 v42, 0xbfb8aa3b, v44
	v_mul_f32_e32 v43, 0xbfb8aa3b, v45
	v_exp_f32_e32 v42, v42
	v_exp_f32_e32 v43, v43
	v_mul_f32_e32 v0, 0xbfb8aa3b, v38
	v_exp_f32_e32 v0, v0
	v_add_f32_e32 v42, 1.0, v42
	v_add_f32_e32 v43, 1.0, v43
	v_rcp_f32_e32 v42, v42
	v_rcp_f32_e32 v43, v43
	v_add_f32_e32 v0, 1.0, v0
	v_cvt_pk_bf16_f32 v46, v46, v47
	v_mad_i64_i32 v[50:51], s[12:13], v58, s15, v[134:135]
	v_pk_mul_f32 v[42:43], v[44:45], v[42:43]
	s_nop 0
	v_pk_mul_f32 v[44:45], v[48:49], v[42:43]
	v_lshl_add_u64 v[42:43], v[50:51], 0, s[10:11]
	v_cvt_pk_bf16_f32 v47, v44, v45
	v_rcp_f32_e32 v44, v0
	v_mul_f32_e32 v0, 0xbfb8aa3b, v39
	v_exp_f32_e32 v0, v0
	global_store_dwordx2 v[42:43], v[46:47], off
	v_add_f32_e32 v0, 1.0, v0
	v_rcp_f32_e32 v45, v0
	v_mul_f32_e32 v0, 0xbfb8aa3b, v40
	v_exp_f32_e32 v0, v0
	v_pk_mul_f32 v[38:39], v[38:39], v[44:45]
	s_nop 0
	v_pk_mul_f32 v[34:35], v[34:35], v[38:39]
	v_add_f32_e32 v0, 1.0, v0
	v_rcp_f32_e32 v38, v0
	v_mul_f32_e32 v0, 0xbfb8aa3b, v41
	v_exp_f32_e32 v0, v0
	v_cvt_pk_bf16_f32 v34, v34, v35
	v_add_f32_e32 v0, 1.0, v0
	v_rcp_f32_e32 v39, v0
	s_nop 0
	v_pk_mul_f32 v[38:39], v[40:41], v[38:39]
	s_nop 0
	v_pk_mul_f32 v[36:37], v[36:37], v[38:39]
	s_nop 0
	v_cvt_pk_bf16_f32 v35, v36, v37
	global_store_dwordx2 v[42:43], v[34:35], off offset:128
	v_add_u32_e32 v42, 0xa0, v136
	v_ashrrev_i32_e32 v43, 31, v42
	v_lshlrev_b64 v[34:35], 5, v[42:43]
	v_lshl_add_u64 v[38:39], s[4:5], 0, v[34:35]
	s_nop 0
	s_waitcnt vmcnt(2)
; #define TIDX launder((int)threadIdx.x)
;     ...
;     float rowss[2][4];
;     const int lane_e = TIDX & 63, fr_e = lane_e & 15, fq_e = lane_e >> 4;
; #pragma unroll
;     for (int ai = 0; ai < 2; ++ai)
; #pragma unroll
;       for (int m = 0; m < 4; ++m) {
;         const int row = brow + ai * HALF + wr * 64 + m * 16 + fr_e;
;         const float rsc = epi.rowscale(row);
;         float ssq = 0.f;
; #pragma unroll
;         for (int bj = 0; bj < 2; ++bj)
;           ssq += epi(row, bcol + bj * HALF + wc * 32, fq_e, acc[ai][bj][m][0] * rsc, acc[ai][bj][m][1] * rsc);
;         rowss[ai][m] = ssq;
;         __builtin_amdgcn_sched_barrier(0);
;       }
;     ...
;     __syncthreads();
;   }
	v_mov_b32_e32 v44, v224
	v_mov_b32_e32 v45, v228
	v_mov_b32_e32 v228, v225
	v_pk_add_f32 v[224:225], v[44:45], v[228:229]
	v_mov_b32_e32 v228, v226
	v_mov_b32_e32 v229, v230
	v_mov_b32_e32 v230, v227
	v_pk_add_f32 v[226:227], v[228:229], v[230:231]
	s_nop 0
	v_pk_add_f32 v[224:225], v[224:225], v[226:227]
	s_nop 0
	v_add_f32_e32 v0, v224, v225
	v_fmamk_f32 v0, v0, 0x3a000000, v249
	v_cmp_gt_f32_e32 vcc, s14, v0
	v_mul_f32_e32 v34, 0x4b800000, v0
	s_nop 0
	v_cndmask_b32_e32 v0, v0, v34, vcc
	v_rsq_f32_e32 v0, v0
	s_nop 0
	v_mul_f32_e32 v34, 0x45800000, v0
	v_cndmask_b32_e32 v0, v0, v34, vcc
	v_pk_mul_f32 v[26:27], v[26:27], v[0:1] op_sel_hi:[1,0]
	v_pk_mul_f32 v[28:29], v[28:29], v[0:1] op_sel_hi:[1,0]
	v_mul_f32_e32 v36, 0xbfb8aa3b, v26
	v_mul_f32_e32 v37, 0xbfb8aa3b, v27
	v_exp_f32_e32 v36, v36
	v_exp_f32_e32 v37, v37
	v_pk_mul_f32 v[30:31], v[30:31], v[0:1] op_sel_hi:[1,0]
	v_pk_mul_f32 v[22:23], v[22:23], v[0:1] op_sel_hi:[1,0]
	v_add_f32_e32 v36, 1.0, v36
	v_add_f32_e32 v37, 1.0, v37
	v_rcp_f32_e32 v36, v36
	v_rcp_f32_e32 v37, v37
	v_pk_mul_f32 v[32:33], v[32:33], v[0:1] op_sel_hi:[1,0]
	v_pk_mul_f32 v[24:25], v[24:25], v[0:1] op_sel_hi:[1,0]
	v_pk_mul_f32 v[20:21], v[20:21], v[0:1] op_sel_hi:[1,0]
	v_pk_mul_f32 v[26:27], v[26:27], v[36:37]
	v_pk_mul_f32 v[18:19], v[18:19], v[0:1] op_sel_hi:[1,0]
	v_pk_mul_f32 v[30:31], v[30:31], v[26:27]
	v_mul_f32_e32 v26, 0xbfb8aa3b, v28
	v_mul_f32_e32 v27, 0xbfb8aa3b, v29
	v_exp_f32_e32 v26, v26
	v_exp_f32_e32 v27, v27
	v_mul_f32_e32 v0, 0xbfb8aa3b, v22
	v_exp_f32_e32 v0, v0
	v_add_f32_e32 v26, 1.0, v26
	v_add_f32_e32 v27, 1.0, v27
	v_rcp_f32_e32 v26, v26
	v_rcp_f32_e32 v27, v27
	v_add_f32_e32 v0, 1.0, v0
	v_cvt_pk_bf16_f32 v30, v30, v31
	v_mad_i64_i32 v[34:35], s[12:13], v42, s15, v[134:135]
	v_pk_mul_f32 v[26:27], v[28:29], v[26:27]
	s_nop 0
	v_pk_mul_f32 v[28:29], v[32:33], v[26:27]
	v_lshl_add_u64 v[26:27], v[34:35], 0, s[10:11]
	v_cvt_pk_bf16_f32 v31, v28, v29
	v_rcp_f32_e32 v28, v0
	v_mul_f32_e32 v0, 0xbfb8aa3b, v23
	v_exp_f32_e32 v0, v0
	global_store_dwordx2 v[26:27], v[30:31], off
	v_add_f32_e32 v0, 1.0, v0
	v_rcp_f32_e32 v29, v0
	v_mul_f32_e32 v0, 0xbfb8aa3b, v24
	v_exp_f32_e32 v0, v0
	v_pk_mul_f32 v[22:23], v[22:23], v[28:29]
	s_nop 0
	v_pk_mul_f32 v[18:19], v[18:19], v[22:23]
	v_add_f32_e32 v0, 1.0, v0
	v_rcp_f32_e32 v22, v0
	v_mul_f32_e32 v0, 0xbfb8aa3b, v25
	v_exp_f32_e32 v0, v0
	v_cvt_pk_bf16_f32 v18, v18, v19
	v_add_f32_e32 v0, 1.0, v0
	v_rcp_f32_e32 v23, v0
	s_nop 0
	v_pk_mul_f32 v[22:23], v[24:25], v[22:23]
	s_nop 0
	v_pk_mul_f32 v[20:21], v[20:21], v[22:23]
	s_nop 0
	v_cvt_pk_bf16_f32 v19, v20, v21
	global_store_dwordx2 v[26:27], v[18:19], off offset:128
	v_add_u32_e32 v26, 0xb0, v136
	v_ashrrev_i32_e32 v27, 31, v26
	v_lshlrev_b64 v[18:19], 5, v[26:27]
	v_lshl_add_u64 v[22:23], s[4:5], 0, v[18:19]
	s_nop 0
	s_mov_b32 s84, 0x800000
	s_waitcnt vmcnt(0)
	v_mov_b32_e32 v28, v232
	v_mov_b32_e32 v29, v236
	v_mov_b32_e32 v236, v233
	v_pk_add_f32 v[232:233], v[28:29], v[236:237]
	v_mov_b32_e32 v236, v234
	v_mov_b32_e32 v237, v238
	v_mov_b32_e32 v238, v235
	v_pk_add_f32 v[234:235], v[236:237], v[238:239]
	s_nop 0
	v_pk_add_f32 v[232:233], v[232:233], v[234:235]
	s_nop 0
	v_add_f32_e32 v0, v232, v233
	v_fmamk_f32 v0, v0, 0x3a000000, v249
	v_cmp_gt_f32_e32 vcc, s14, v0
	v_mul_f32_e32 v18, 0x4b800000, v0
	s_nop 0
	v_cndmask_b32_e32 v0, v0, v18, vcc
	v_rsq_f32_e32 v0, v0
	s_nop 0
	v_mul_f32_e32 v18, 0x45800000, v0
	v_cndmask_b32_e32 v0, v0, v18, vcc
	v_pk_mul_f32 v[10:11], v[10:11], v[0:1] op_sel_hi:[1,0]
	v_pk_mul_f32 v[12:13], v[12:13], v[0:1] op_sel_hi:[1,0]
	v_mul_f32_e32 v20, 0xbfb8aa3b, v10
	v_mul_f32_e32 v21, 0xbfb8aa3b, v11
	v_exp_f32_e32 v20, v20
	v_exp_f32_e32 v21, v21
	v_pk_mul_f32 v[14:15], v[14:15], v[0:1] op_sel_hi:[1,0]
	v_pk_mul_f32 v[6:7], v[6:7], v[0:1] op_sel_hi:[1,0]
	v_add_f32_e32 v20, 1.0, v20
	v_add_f32_e32 v21, 1.0, v21
	v_rcp_f32_e32 v20, v20
	v_rcp_f32_e32 v21, v21
	v_pk_mul_f32 v[16:17], v[16:17], v[0:1] op_sel_hi:[1,0]
	v_pk_mul_f32 v[8:9], v[8:9], v[0:1] op_sel_hi:[1,0]
	v_pk_mul_f32 v[4:5], v[4:5], v[0:1] op_sel_hi:[1,0]
	v_pk_mul_f32 v[10:11], v[10:11], v[20:21]
	v_pk_mul_f32 v[2:3], v[2:3], v[0:1] op_sel_hi:[1,0]
	v_pk_mul_f32 v[14:15], v[14:15], v[10:11]
	v_mul_f32_e32 v10, 0xbfb8aa3b, v12
	v_mul_f32_e32 v11, 0xbfb8aa3b, v13
	v_exp_f32_e32 v10, v10
	v_exp_f32_e32 v11, v11
	v_mul_f32_e32 v0, 0xbfb8aa3b, v6
	v_exp_f32_e32 v0, v0
	v_add_f32_e32 v10, 1.0, v10
	v_add_f32_e32 v11, 1.0, v11
	v_rcp_f32_e32 v10, v10
	v_rcp_f32_e32 v11, v11
	v_add_f32_e32 v0, 1.0, v0
	v_cvt_pk_bf16_f32 v14, v14, v15
	v_mad_i64_i32 v[18:19], s[12:13], v26, s15, v[134:135]
	v_pk_mul_f32 v[10:11], v[12:13], v[10:11]
	s_nop 0
	v_pk_mul_f32 v[12:13], v[16:17], v[10:11]
	v_lshl_add_u64 v[10:11], v[18:19], 0, s[10:11]
	v_cvt_pk_bf16_f32 v15, v12, v13
	v_rcp_f32_e32 v12, v0
	v_mul_f32_e32 v0, 0xbfb8aa3b, v7
	v_exp_f32_e32 v0, v0
	global_store_dwordx2 v[10:11], v[14:15], off
	v_add_f32_e32 v0, 1.0, v0
	v_rcp_f32_e32 v13, v0
	v_mul_f32_e32 v0, 0xbfb8aa3b, v8
	v_exp_f32_e32 v0, v0
	v_pk_mul_f32 v[6:7], v[6:7], v[12:13]
	s_nop 0
	v_pk_mul_f32 v[2:3], v[2:3], v[6:7]
	v_add_f32_e32 v0, 1.0, v0
	v_rcp_f32_e32 v6, v0
	v_mul_f32_e32 v0, 0xbfb8aa3b, v9
	v_exp_f32_e32 v0, v0
	v_cvt_pk_bf16_f32 v2, v2, v3
	v_add_f32_e32 v0, 1.0, v0
	v_rcp_f32_e32 v7, v0
	s_nop 0
	v_pk_mul_f32 v[6:7], v[8:9], v[6:7]
	s_nop 0
	v_pk_mul_f32 v[4:5], v[4:5], v[6:7]
	s_nop 0
	v_cvt_pk_bf16_f32 v3, v4, v5
	global_store_dwordx2 v[10:11], v[2:3], off offset:128
	v_readlane_b32 s10, v250, 1
	s_add_i32 s31, s31, s10
	s_cmpk_gt_i32 s31, 0x57f
	s_barrier
	v_readlane_b32 s11, v250, 2
	s_cbranch_scc1 .LBB0_31
	s_branch .Lpf_setup

; #define G_STAGE(bufoff, gbase, voff) do { _Pragma("unroll") for (int _i = 0; _i < 2; ++_i) \
;     __builtin_amdgcn_global_load_lds((const unsigned*)(uniform_ptr((const char*)(gbase)) + (voff)[_i]), (LAS unsigned*)(lds + (bufoff) + ldsw + _i * 8192), 16, 0, 0); } while (0)
; #define BAR __builtin_amdgcn_s_barrier()
;     ...
;   for (int u = (int)((blockIdx.x + gridDim.x - blk_off) % gridDim.x); u < nwg; u += gridDim.x) {
;     int wgid = u;
;     { int q = nwg / NXCD, r = nwg % NXCD, xcd = wgid % NXCD, off = wgid / NXCD; wgid = (xcd < r ? xcd * (q + 1) : r * (q + 1) + (xcd - r) * q) + off; }
;     int nig = WGM * nN, gid = wgid / nig, fm = gid * WGM, gsz = min(nM - fm, WGM);
;     const int pm = __builtin_amdgcn_readfirstlane(fm + ((wgid % nig) % gsz)), pn = __builtin_amdgcn_readfirstlane((wgid % nig) / gsz), brow = pm * BM, bcol = pn * BM;
;     f32x4 acc[2][2][4][2];
; #pragma unroll
;     for (int a = 0; a < 2; ++a)
; #pragma unroll
;       for (int b = 0; b < 2; ++b)
; #pragma unroll
;         for (int m = 0; m < 4; ++m)
; #pragma unroll
;           for (int n = 0; n < 2; ++n) acc[a][b][m][n] = (f32x4){0.f, 0.f, 0.f, 0.f};
;     bf16x8 At[4][2], B0[2][2], B1[2][2];
;     const char* cA = (const char*)A + (size_t)brow * lda * 2; const char* cB = (const char*)Bt + (size_t)bcol * ldb * 2;
;     G_STAGE(G_SB(0, 0), cB, voffB); G_STAGE(G_SA(0, 0), cA, voffA); G_STAGE(G_SB(0, 1), cB + hstepB, voffB); G_STAGE(G_SA(0, 1), cA + hstepA, voffA);
;     if (wr == 1) BAR;
.Lpf_setup:
	s_ashr_i32 s10, s31, 31
	s_lshr_b32 s10, s10, 29
	s_add_i32 s10, s31, s10
	s_ashr_i32 s11, s10, 3
	s_and_b32 s10, s10, -8
	s_sub_i32 s10, s31, s10
	s_cmp_lt_i32 s10, 0
	s_movk_i32 s12, 0xb1
	s_cselect_b32 s12, s12, 0xb0
	s_mul_i32 s10, s12, s10
	s_add_i32 s10, s10, s11
	s_mul_hi_i32 s11, s10, 0x2e8ba2e9
	s_lshr_b32 s12, s11, 31
	s_ashr_i32 s11, s11, 6
	s_add_i32 s11, s11, s12
	s_lshl_b32 s12, s11, 3
	s_mulk_i32 s11, 0x160
	s_sub_i32 s10, s10, s11
	s_bfe_u32 s11, s10, 0x3001c
	s_add_i32 s11, s10, s11
	s_and_b32 s13, s11, 0xfff8
	s_sub_i32 s10, s10, s13
	s_sext_i32_i16 s10, s10
	s_sext_i32_i16 s11, s11
	s_add_i32 s12, s12, s10
	s_lshl_b32 s11, s11, 5
	s_lshl_b32 s10, s12, 8
	s_and_b32 s12, s11, 0xffffff00
	s_ashr_i32 s11, s10, 31
	s_ashr_i32 s13, s12, 31
	s_lshl_b64 s[18:19], s[10:11], 12
	s_lshl_b64 s[16:17], s[12:13], 12
	s_add_u32 s20, s22, s16
	s_addc_u32 s21, s23, s17
	s_add_i32 s11, s26, 0
	v_lshl_add_u64 v[2:3], s[20:21], 0, v[132:133]
	s_add_i32 m0, s11, 0x10000
	v_readlane_b32 s14, v253, 54
	s_add_i32 m0, s11, 0x12000
	v_readlane_b32 s15, v253, 55
	s_add_u32 s14, s14, s18
	v_lshl_add_u64 v[2:3], s[20:21], 0, v[130:131]
	s_addc_u32 s15, s15, s19
	s_add_i32 s13, s11, 0x2000
	v_lshl_add_u64 v[2:3], s[14:15], 0, v[132:133]
	s_mov_b32 m0, s11
	s_add_u32 s34, s20, 0x80000
	v_lshl_add_u64 v[2:3], s[14:15], 0, v[130:131]
	s_mov_b32 m0, s13
	s_addc_u32 s35, s21, 0
	v_lshl_add_u64 v[2:3], s[34:35], 0, v[132:133]
	s_add_i32 m0, s11, 0x14000
	s_nop 0
	s_add_i32 m0, s11, 0x16000
	v_lshl_add_u64 v[2:3], s[34:35], 0, v[130:131]
	s_add_u32 s34, s14, 0x80000
	s_addc_u32 s35, s15, 0
	s_add_i32 s33, s11, 0x4000
	v_lshl_add_u64 v[2:3], s[34:35], 0, v[132:133]
	s_mov_b32 m0, s33
	s_andn2_b64 vcc, exec, s[6:7]
	v_lshl_add_u64 v[2:3], s[34:35], 0, v[130:131]
	s_add_i32 s34, s11, 0x6000
	s_mov_b32 m0, s34
	s_nop 0
	s_cbranch_vccnz .LBB0_24
	s_barrier
	s_branch .LBB0_24

; DI int crow(int i, int g) { return (i & 3) + 8 * (i >> 2) + 4 * g; }
; DI bf16x8 pack8(const float* p) { u32x4 o; o.x = pk2h(p[0], p[1]); o.y = pk2h(p[2], p[3]); o.z = pk2h(p[4], p[5]); o.w = pk2h(p[6], p[7]); return __builtin_bit_cast(bf16x8, o); }
; DI void hgrn_out_task(const Params& p, int e, int bh, int c, int tt) {
;     ...
;   for (int st = 0; st <= tt; ++st) {
;     f32x16 acc = score_tile(qf, KT + (size_t)st * 32 * 128, koff);
;     float a[16];
; #pragma unroll
;     for (int i = 0; i < 16; ++i) a[i] = (st < tt || crow(i, g) <= lr) ? acc[i] : 0.f;
;     bf16x8 pf[2]; pf[0] = pack8(a); pf[1] = pack8(a + 8);
;     pv_tile(o, pf, VT + (size_t)st * 4096, 32, voffT);
;   }
.LBB0_283:
	v_lshl_add_u64 v[140:141], v[130:131], 0, s[56:57]
	global_load_dwordx4 v[66:69], v[140:141], off offset:-128
	global_load_dwordx4 v[136:139], v[140:141], off offset:-96
	v_cmp_lt_u32_e64 s[34:35], s33, v119
	s_or_b64 s[36:37], s[34:35], vcc
	s_add_i32 s33, s33, 1
	s_waitcnt vmcnt(1)
	v_mfma_f32_32x32x16_bf16 v[66:81], v[66:69], v[82:85], 0
	s_waitcnt vmcnt(0)
	v_mfma_f32_32x32x16_bf16 v[66:81], v[136:139], v[86:89], v[66:81]
	global_load_dwordx4 v[136:139], v[140:141], off offset:-64
	s_waitcnt vmcnt(0)
	v_mfma_f32_32x32x16_bf16 v[66:81], v[136:139], v[90:93], v[66:81]
	global_load_dwordx4 v[136:139], v[140:141], off offset:-32
	s_waitcnt vmcnt(0)
	v_mfma_f32_32x32x16_bf16 v[66:81], v[136:139], v[94:97], v[66:81]
	global_load_dwordx4 v[136:139], v[140:141], off
	s_waitcnt vmcnt(0)
	v_mfma_f32_32x32x16_bf16 v[66:81], v[136:139], v[98:101], v[66:81]
	global_load_dwordx4 v[136:139], v[140:141], off offset:32
	s_waitcnt vmcnt(0)
	v_mfma_f32_32x32x16_bf16 v[66:81], v[136:139], v[102:105], v[66:81]
	global_load_dwordx4 v[136:139], v[140:141], off offset:64
	s_waitcnt vmcnt(0)
	v_mfma_f32_32x32x16_bf16 v[66:81], v[136:139], v[106:109], v[66:81]
	global_load_dwordx4 v[136:139], v[140:141], off offset:96
	s_waitcnt vmcnt(0)
	v_mfma_f32_32x32x16_bf16 v[66:81], v[136:139], v[110:113], v[66:81]
	s_nop 11
	v_cndmask_b32_e64 v0, 0, v66, s[36:37]
	s_or_b64 s[36:37], s[34:35], s[0:1]
	v_cndmask_b32_e64 v66, 0, v67, s[36:37]
	s_or_b64 s[36:37], s[34:35], s[30:31]
	v_cndmask_b32_e64 v67, 0, v68, s[36:37]
	s_or_b64 s[36:37], s[34:35], s[4:5]
	v_cndmask_b32_e64 v68, 0, v69, s[36:37]
	s_or_b64 s[36:37], s[34:35], s[6:7]
	v_cndmask_b32_e64 v69, 0, v70, s[36:37]
	s_or_b64 s[36:37], s[34:35], s[8:9]
	v_cndmask_b32_e64 v127, 0, v71, s[36:37]
	s_or_b64 s[36:37], s[34:35], s[10:11]
	v_cndmask_b32_e64 v136, 0, v72, s[36:37]
	s_or_b64 s[36:37], s[34:35], s[12:13]
	v_cndmask_b32_e64 v73, 0, v73, s[36:37]
	s_or_b64 s[36:37], s[34:35], s[14:15]
	v_cndmask_b32_e64 v74, 0, v74, s[36:37]
	s_or_b64 s[36:37], s[34:35], s[16:17]
	v_cndmask_b32_e64 v75, 0, v75, s[36:37]
	s_or_b64 s[36:37], s[34:35], s[18:19]
	v_cndmask_b32_e64 v76, 0, v76, s[36:37]
	s_or_b64 s[36:37], s[34:35], s[20:21]
	v_cndmask_b32_e64 v77, 0, v77, s[36:37]
	s_or_b64 s[36:37], s[34:35], s[22:23]
	v_cndmask_b32_e64 v78, 0, v78, s[36:37]
	s_or_b64 s[36:37], s[34:35], s[24:25]
	v_cndmask_b32_e64 v79, 0, v79, s[36:37]
	s_or_b64 s[36:37], s[34:35], s[26:27]
	s_or_b64 s[34:35], s[34:35], s[28:29]
	v_cndmask_b32_e64 v80, 0, v80, s[36:37]
	v_cndmask_b32_e64 v81, 0, v81, s[34:35]
	v_cvt_pk_bf16_f32 v70, v0, v66
	v_cvt_pk_bf16_f32 v66, v74, v75
	v_lshl_add_u64 v[74:75], v[134:135], 0, s[56:57]
	s_mov_b32 s34, 0x2b145000
	v_cvt_pk_bf16_f32 v72, v69, v127
	v_cvt_pk_bf16_f32 v69, v80, v81
	v_add_co_u32_e64 v80, s[34:35], s34, v74
	v_cvt_pk_bf16_f32 v71, v67, v68
	s_nop 0
	v_addc_co_u32_e64 v81, s[34:35], 0, v75, s[34:35]
	s_mov_b32 s34, 0x2b146000
	s_nop 0
	v_add_co_u32_e64 v74, s[34:35], s34, v74
	v_cvt_pk_bf16_f32 v67, v76, v77
	s_nop 0
	v_addc_co_u32_e64 v75, s[34:35], 0, v75, s[34:35]
	v_cvt_pk_bf16_f32 v68, v78, v79
	global_load_dwordx2 v[76:77], v[74:75], off offset:-4096
	global_load_dwordx2 v[78:79], v[80:81], off offset:16
	v_cvt_pk_bf16_f32 v73, v136, v73
	s_waitcnt vmcnt(0)
	s_nop 0
	v_mfma_f32_32x32x16_bf16 v[50:65], v[76:79], v[70:73], v[50:65]
	global_load_dwordx2 v[76:77], v[80:81], off offset:32
	global_load_dwordx2 v[78:79], v[80:81], off offset:48
	s_waitcnt vmcnt(0)
	v_mfma_f32_32x32x16_bf16 v[50:65], v[76:79], v[66:69], v[50:65]
	global_load_dwordx2 v[76:77], v[80:81], off offset:2048
	global_load_dwordx2 v[78:79], v[80:81], off offset:2064
	s_waitcnt vmcnt(0)
	v_mfma_f32_32x32x16_bf16 v[34:49], v[76:79], v[70:73], v[34:49]
	global_load_dwordx2 v[76:77], v[80:81], off offset:2080
	global_load_dwordx2 v[78:79], v[80:81], off offset:2096
	s_waitcnt vmcnt(0)
	v_mfma_f32_32x32x16_bf16 v[34:49], v[76:79], v[66:69], v[34:49]
	global_load_dwordx2 v[76:77], v[74:75], off
	global_load_dwordx2 v[78:79], v[74:75], off offset:16
	s_waitcnt vmcnt(0)
	v_mfma_f32_32x32x16_bf16 v[18:33], v[76:79], v[70:73], v[18:33]
	v_lshl_add_u64 v[76:77], v[132:133], 0, s[56:57]
	global_load_dwordx2 v[78:79], v[76:77], off offset:-2048
	global_load_dwordx2 v[80:81], v[76:77], off offset:-2032
	s_add_u32 s56, s56, 0x2000
	s_addc_u32 s57, s57, 0
	v_cmp_eq_u32_e64 s[34:35], s56, v116
	s_or_b64 s[54:55], s[34:35], s[54:55]
	s_waitcnt vmcnt(0)
	v_mfma_f32_32x32x16_bf16 v[18:33], v[78:81], v[66:69], v[18:33]
	global_load_dwordx2 v[78:79], v[74:75], off offset:2048
	global_load_dwordx2 v[80:81], v[74:75], off offset:2064
	s_waitcnt vmcnt(0)
	v_mfma_f32_32x32x16_bf16 v[2:17], v[78:81], v[70:73], v[2:17]
	global_load_dwordx2 v[70:71], v[76:77], off
	global_load_dwordx2 v[72:73], v[76:77], off offset:16
	s_waitcnt vmcnt(0)
	v_mfma_f32_32x32x16_bf16 v[2:17], v[70:73], v[66:69], v[2:17]
	s_andn2_b64 exec, exec, s[54:55]
	s_cbranch_execnz .LBB0_283
; DI f32x16 mfma32(bf16x8 a, bf16x8 b, f32x16 c) { return __builtin_amdgcn_mfma_f32_32x32x16_bf16(a, b, c, 0, 0, 0); }
; DI void hgrn_out_task(const Params& p, int e, int bh, int c, int tt) {
;     ...
;   load_q_raw(qf, QS + (size_t)(tt * 32 + lr) * 128, g);
; #pragma unroll
;   for (int vt = 0; vt < 4; ++vt) {
;     const bf16_t* sr = ST + (size_t)(vt * 32 + lr) * 128 + g * 8;
; #pragma unroll
;     for (int ks = 0; ks < 8; ++ks) { const bf16x8 a = *(const bf16x8*)(sr + ks * 16); o[vt] = mfma32(a, qf[ks], o[vt]); }
;   }
;   float ss = 0.f;
; #pragma unroll
;   for (int vt = 0; vt < 4; ++vt)
; #pragma unroll
;     for (int i = 0; i < 16; ++i) ss += o[vt][i] * o[vt][i];
	s_or_b64 exec, exec, s[54:55]
	v_lshlrev_b64 v[66:67], 21, v[122:123]
	v_lshl_add_u64 v[66:67], s[40:41], 0, v[66:67]
	v_lshlrev_b32_e32 v0, 15, v121
	v_lshl_add_u64 v[68:69], v[128:129], 1, s[42:43]
	v_lshl_add_u64 v[100:101], v[66:67], 0, v[0:1]
	v_lshlrev_b32_e32 v0, 1, v126
	v_lshl_add_u64 v[66:67], v[68:69], 0, v[0:1]
	v_lshlrev_b32_e32 v0, 1, v124
	v_lshl_add_u64 v[100:101], v[100:101], 0, v[0:1]
	v_mov_b32_e32 v121, v1
	v_lshl_add_u64 v[66:67], v[66:67], 0, v[0:1]
	v_lshl_add_u64 v[100:101], v[100:101], 0, v[120:121]
	global_load_dwordx4 v[94:97], v[66:67], off
	global_load_dwordx4 v[90:93], v[66:67], off offset:32
	global_load_dwordx4 v[86:89], v[66:67], off offset:64
	global_load_dwordx4 v[82:85], v[66:67], off offset:96
	global_load_dwordx4 v[78:81], v[66:67], off offset:128
	global_load_dwordx4 v[74:77], v[66:67], off offset:160
	global_load_dwordx4 v[70:73], v[66:67], off offset:192
	s_nop 0
	global_load_dwordx4 v[66:69], v[66:67], off offset:224
	v_ashrrev_i32_e32 v98, 10, v115
	v_ashrrev_i32_e32 v99, 31, v98
	v_readlane_b32 s34, v253, 48
	v_readlane_b32 s35, v253, 49
	s_mov_b64 s[0:1], 0x23081800
	v_add_co_u32_e32 v216, vcc, 0x2000, v100
	s_nop 1
	v_addc_co_u32_e32 v217, vcc, 0, v101, vcc
	v_add_co_u32_e32 v218, vcc, 0x4000, v100
	s_nop 1
	v_addc_co_u32_e32 v219, vcc, 0, v101, vcc
	v_add_co_u32_e32 v220, vcc, 0x6000, v100
	s_nop 1
	v_addc_co_u32_e32 v221, vcc, 0, v101, vcc
	global_load_dwordx4 v[142:145], v[100:101], off
	global_load_dwordx4 v[146:149], v[100:101], off offset:32
	global_load_dwordx4 v[150:153], v[100:101], off offset:64
	global_load_dwordx4 v[154:157], v[100:101], off offset:96
	global_load_dwordx4 v[158:161], v[100:101], off offset:128
	global_load_dwordx4 v[162:165], v[100:101], off offset:160
	global_load_dwordx4 v[166:169], v[100:101], off offset:192
	global_load_dwordx4 v[170:173], v[100:101], off offset:224
	global_load_dwordx4 v[174:177], v[216:217], off
	global_load_dwordx4 v[178:181], v[216:217], off offset:32
	global_load_dwordx4 v[182:185], v[216:217], off offset:64
	global_load_dwordx4 v[186:189], v[216:217], off offset:96
	global_load_dwordx4 v[200:203], v[216:217], off offset:128
	global_load_dwordx4 v[204:207], v[216:217], off offset:160
	global_load_dwordx4 v[208:211], v[216:217], off offset:192
	global_load_dwordx4 v[212:215], v[216:217], off offset:224
	s_waitcnt vmcnt(15)
	v_mfma_f32_32x32x16_bf16 v[50:65], v[142:145], v[94:97], v[50:65]
	s_waitcnt vmcnt(14)
	v_mfma_f32_32x32x16_bf16 v[50:65], v[146:149], v[90:93], v[50:65]
	s_waitcnt vmcnt(13)
	v_mfma_f32_32x32x16_bf16 v[50:65], v[150:153], v[86:89], v[50:65]
	s_waitcnt vmcnt(12)
	v_mfma_f32_32x32x16_bf16 v[50:65], v[154:157], v[82:85], v[50:65]
	s_waitcnt vmcnt(11)
	v_mfma_f32_32x32x16_bf16 v[50:65], v[158:161], v[78:81], v[50:65]
	s_waitcnt vmcnt(10)
	v_mfma_f32_32x32x16_bf16 v[50:65], v[162:165], v[74:77], v[50:65]
	s_waitcnt vmcnt(9)
	v_mfma_f32_32x32x16_bf16 v[50:65], v[166:169], v[70:73], v[50:65]
	s_waitcnt vmcnt(8)
	v_mfma_f32_32x32x16_bf16 v[50:65], v[170:173], v[66:69], v[50:65]
	global_load_dwordx4 v[142:145], v[218:219], off
	global_load_dwordx4 v[146:149], v[218:219], off offset:32
	global_load_dwordx4 v[150:153], v[218:219], off offset:64
	global_load_dwordx4 v[154:157], v[218:219], off offset:96
	global_load_dwordx4 v[158:161], v[218:219], off offset:128
	global_load_dwordx4 v[162:165], v[218:219], off offset:160
	global_load_dwordx4 v[166:169], v[218:219], off offset:192
	global_load_dwordx4 v[170:173], v[218:219], off offset:224
	s_nop 3
	v_mul_f32_e32 v0, v51, v51
	v_fmac_f32_e32 v0, v50, v50
	v_fmac_f32_e32 v0, v52, v52
	v_fmac_f32_e32 v0, v53, v53
	v_fmac_f32_e32 v0, v54, v54
	v_fmac_f32_e32 v0, v55, v55
	v_fmac_f32_e32 v0, v56, v56
	v_fmac_f32_e32 v0, v57, v57
	v_fmac_f32_e32 v0, v58, v58
	v_fmac_f32_e32 v0, v59, v59
	v_fmac_f32_e32 v0, v60, v60
	v_fmac_f32_e32 v0, v61, v61
	v_fmac_f32_e32 v0, v62, v62
	v_fmac_f32_e32 v0, v63, v63
	v_fmac_f32_e32 v0, v64, v64
	v_fmac_f32_e32 v0, v65, v65
	s_waitcnt vmcnt(15)
	v_mfma_f32_32x32x16_bf16 v[34:49], v[174:177], v[94:97], v[34:49]
	s_waitcnt vmcnt(14)
	v_mfma_f32_32x32x16_bf16 v[34:49], v[178:181], v[90:93], v[34:49]
	s_waitcnt vmcnt(13)
	v_mfma_f32_32x32x16_bf16 v[34:49], v[182:185], v[86:89], v[34:49]
	s_waitcnt vmcnt(12)
	v_mfma_f32_32x32x16_bf16 v[34:49], v[186:189], v[82:85], v[34:49]
	s_waitcnt vmcnt(11)
	v_mfma_f32_32x32x16_bf16 v[34:49], v[200:203], v[78:81], v[34:49]
	s_waitcnt vmcnt(10)
	v_mfma_f32_32x32x16_bf16 v[34:49], v[204:207], v[74:77], v[34:49]
	s_waitcnt vmcnt(9)
	v_mfma_f32_32x32x16_bf16 v[34:49], v[208:211], v[70:73], v[34:49]
	s_waitcnt vmcnt(8)
	v_mfma_f32_32x32x16_bf16 v[34:49], v[212:215], v[66:69], v[34:49]
	global_load_dwordx4 v[174:177], v[220:221], off
	global_load_dwordx4 v[178:181], v[220:221], off offset:32
	global_load_dwordx4 v[182:185], v[220:221], off offset:64
	global_load_dwordx4 v[186:189], v[220:221], off offset:96
	global_load_dwordx4 v[200:203], v[220:221], off offset:128
	global_load_dwordx4 v[204:207], v[220:221], off offset:160
	global_load_dwordx4 v[208:211], v[220:221], off offset:192
	global_load_dwordx4 v[212:215], v[220:221], off offset:224
	s_nop 3
	v_fmac_f32_e32 v0, v34, v34
	v_fmac_f32_e32 v0, v35, v35
	v_fmac_f32_e32 v0, v36, v36
	v_fmac_f32_e32 v0, v37, v37
	v_fmac_f32_e32 v0, v38, v38
	v_fmac_f32_e32 v0, v39, v39
	v_fmac_f32_e32 v0, v40, v40
	v_fmac_f32_e32 v0, v41, v41
	v_fmac_f32_e32 v0, v42, v42
	v_fmac_f32_e32 v0, v43, v43
	v_fmac_f32_e32 v0, v44, v44
	v_fmac_f32_e32 v0, v45, v45
	v_fmac_f32_e32 v0, v46, v46
	v_fmac_f32_e32 v0, v47, v47
	v_fmac_f32_e32 v0, v48, v48
	v_fmac_f32_e32 v0, v49, v49
	s_waitcnt vmcnt(15)
; DI float bf2f(bf16_t v) { return __uint_as_float(((unsigned)v) << 16); }
; DI float xhalf_sum(float v) { const auto r = __builtin_amdgcn_permlane32_swap(__float_as_uint(v), __float_as_uint(v), false, false); return __uint_as_float(r[0]) + __uint_as_float(r[1]); }
; DI float frcp(float x) { return __builtin_amdgcn_rcpf(x); }
; DI f32x16 mfma32(bf16x8 a, bf16x8 b, f32x16 c) { return __builtin_amdgcn_mfma_f32_32x32x16_bf16(a, b, c, 0, 0, 0); }
; DI void st_bf16x4(bf16_t* p, f32x4 v) { u32x2 o; o.x = pk2e(v[0], v[1]); o.y = pk2e(v[2], v[3]); *(u32x2*)p = o; }
; DI void hgrn_out_task(const Params& p, int e, int bh, int c, int tt) {
;     ...
;   for (int vt = 0; vt < 4; ++vt) {
;     const bf16_t* sr = ST + (size_t)(vt * 32 + lr) * 128 + g * 8;
; #pragma unroll
;     for (int ks = 0; ks < 8; ++ks) { const bf16x8 a = *(const bf16x8*)(sr + ks * 16); o[vt] = mfma32(a, qf[ks], o[vt]); }
;   }
;   float ss = 0.f;
; #pragma unroll
;   for (int vt = 0; vt < 4; ++vt)
; #pragma unroll
;     for (int i = 0; i < 16; ++i) ss += o[vt][i] * o[vt][i];
;   ss = xhalf_sum(ss);
;   const float rs = rsqrtf(ss * (1.f / 128.f) + EPS_);
;   const size_t m = (size_t)b * T_ + c * 64 + tt * 32 + lr;
;   const bf16_t* hg = (const bf16_t*)(p.ws + E_HG) + m * 1024 + h * 128;
;   const float* og = p.in[12] + e * 128;
;   bf16_t* orow = (bf16_t*)(p.ws + A_MIXO) + m * D_ + 1024 + h * 128;
; #pragma unroll
;   for (int vt = 0; vt < 4; ++vt)
; #pragma unroll
;     for (int q = 0; q < 4; ++q) {
;       const int d0 = vt * 32 + q * 8 + 4 * g;
;       const s16x4 gv = *(const s16x4*)(hg + d0); const f32x4 gn = *(const f32x4*)(og + d0);
;       f32x4 v;
; #pragma unroll
;       for (int e2 = 0; e2 < 4; ++e2) { const float gg = bf2f((bf16_t)gv[e2]); v[e2] = o[vt][q * 4 + e2] * rs * gn[e2] * (gg * frcp(1.f + __expf(-gg))); }
;       st_bf16x4(orow + d0, v);
	v_mfma_f32_32x32x16_bf16 v[18:33], v[142:145], v[94:97], v[18:33]
	s_waitcnt vmcnt(14)
	v_mfma_f32_32x32x16_bf16 v[18:33], v[146:149], v[90:93], v[18:33]
	s_waitcnt vmcnt(13)
	v_mfma_f32_32x32x16_bf16 v[18:33], v[150:153], v[86:89], v[18:33]
	s_waitcnt vmcnt(12)
	v_mfma_f32_32x32x16_bf16 v[18:33], v[154:157], v[82:85], v[18:33]
	s_waitcnt vmcnt(11)
	v_mfma_f32_32x32x16_bf16 v[18:33], v[158:161], v[78:81], v[18:33]
	s_waitcnt vmcnt(10)
	v_mfma_f32_32x32x16_bf16 v[18:33], v[162:165], v[74:77], v[18:33]
	s_waitcnt vmcnt(9)
	v_mfma_f32_32x32x16_bf16 v[18:33], v[166:169], v[70:73], v[18:33]
	s_waitcnt vmcnt(8)
	v_mfma_f32_32x32x16_bf16 v[18:33], v[170:173], v[66:69], v[18:33]
	s_waitcnt vmcnt(7)
	v_mfma_f32_32x32x16_bf16 v[2:17], v[174:177], v[94:97], v[2:17]
	s_waitcnt vmcnt(6)
	v_mfma_f32_32x32x16_bf16 v[2:17], v[178:181], v[90:93], v[2:17]
	s_waitcnt vmcnt(5)
	v_mfma_f32_32x32x16_bf16 v[2:17], v[182:185], v[86:89], v[2:17]
	s_waitcnt vmcnt(4)
	v_mfma_f32_32x32x16_bf16 v[2:17], v[186:189], v[82:85], v[2:17]
	s_waitcnt vmcnt(3)
	v_mfma_f32_32x32x16_bf16 v[2:17], v[200:203], v[78:81], v[2:17]
	s_waitcnt vmcnt(2)
	v_mfma_f32_32x32x16_bf16 v[2:17], v[204:207], v[74:77], v[2:17]
	s_waitcnt vmcnt(1)
	v_mfma_f32_32x32x16_bf16 v[2:17], v[208:211], v[70:73], v[2:17]
	s_waitcnt vmcnt(0)
	v_mfma_f32_32x32x16_bf16 v[2:17], v[212:215], v[66:69], v[2:17]
	v_fmac_f32_e32 v0, v18, v18
	v_fmac_f32_e32 v0, v19, v19
	v_fmac_f32_e32 v0, v20, v20
	v_fmac_f32_e32 v0, v21, v21
	v_fmac_f32_e32 v0, v22, v22
	v_fmac_f32_e32 v0, v23, v23
	v_fmac_f32_e32 v0, v24, v24
	v_fmac_f32_e32 v0, v25, v25
	v_fmac_f32_e32 v0, v26, v26
	v_fmac_f32_e32 v0, v27, v27
	v_fmac_f32_e32 v0, v28, v28
	v_fmac_f32_e32 v0, v29, v29
	v_fmac_f32_e32 v0, v30, v30
	v_fmac_f32_e32 v0, v31, v31
	v_fmac_f32_e32 v0, v32, v32
	v_fmac_f32_e32 v0, v33, v33
	s_nop 11
	v_fmac_f32_e32 v0, v2, v2
	v_fmac_f32_e32 v0, v3, v3
	v_fmac_f32_e32 v0, v4, v4
	v_fmac_f32_e32 v0, v5, v5
	v_fmac_f32_e32 v0, v6, v6
	v_fmac_f32_e32 v0, v7, v7
	v_fmac_f32_e32 v0, v8, v8
	v_fmac_f32_e32 v0, v9, v9
	v_fmac_f32_e32 v0, v10, v10
	v_fmac_f32_e32 v0, v11, v11
	v_pk_mul_f32 v[70:71], v[12:13], v[12:13]
	v_pk_mul_f32 v[68:69], v[14:15], v[14:15]
	v_add_f32_e32 v0, v70, v0
	v_add_f32_e32 v0, v71, v0
	v_add_f32_e32 v0, v68, v0
	v_pk_mul_f32 v[66:67], v[16:17], v[16:17]
	v_add_f32_e32 v0, v69, v0
	v_add_f32_e32 v0, v66, v0
	v_add_f32_e32 v0, v67, v0
	v_mov_b32_e32 v66, v0
	s_nop 1
	v_permlane32_swap_b32_e32 v0, v66
	v_add_f32_e32 v0, v0, v66
	v_fmamk_f32 v0, v0, 0x3c000000, v249
	v_cmp_gt_f32_e32 vcc, s84, v0
	v_mul_f32_e32 v66, 0x4b800000, v0
	v_lshlrev_b32_e32 v71, 2, v117
	v_cndmask_b32_e32 v0, v0, v66, vcc
	v_rsq_f32_e32 v0, v0
	s_nop 0
	v_mul_f32_e32 v66, 0x45800000, v0
	v_cndmask_b32_e32 v70, v0, v66, vcc
	v_lshlrev_b64 v[66:67], 12, v[98:99]
	v_or_b32_e32 v0, v66, v114
	v_or_b32_e32 v0, v0, v125
	v_or_b32_e32 v66, v0, v118
	v_lshlrev_b64 v[68:69], 11, v[66:67]
	v_and_b32_e32 v0, 0x380, v115
	v_lshlrev_b64 v[66:67], 12, v[66:67]
	v_lshl_add_u64 v[68:69], s[44:45], 0, v[68:69]
	v_lshlrev_b32_e32 v0, 1, v0
	v_lshl_add_u64 v[66:67], s[34:35], 0, v[66:67]
	v_lshl_add_u64 v[68:69], v[68:69], 0, v[0:1]
	v_lshl_add_u64 v[74:75], v[66:67], 0, v[0:1]
	v_lshlrev_b32_e32 v0, 1, v117
	v_lshl_add_u64 v[72:73], v[68:69], 0, v[0:1]
	global_load_dwordx2 v[76:77], v[72:73], off
	global_load_dwordx4 v[66:69], v71, s[46:47]
	v_pk_mul_f32 v[50:51], v[50:51], v[70:71] op_sel_hi:[1,0]
	v_pk_mul_f32 v[52:53], v[52:53], v[70:71] op_sel_hi:[1,0]
	v_pk_mul_f32 v[54:55], v[54:55], v[70:71] op_sel_hi:[1,0]
	v_pk_mul_f32 v[56:57], v[56:57], v[70:71] op_sel_hi:[1,0]
	v_pk_mul_f32 v[58:59], v[58:59], v[70:71] op_sel_hi:[1,0]
	v_pk_mul_f32 v[60:61], v[60:61], v[70:71] op_sel_hi:[1,0]
	v_pk_mul_f32 v[62:63], v[62:63], v[70:71] op_sel_hi:[1,0]
	v_pk_mul_f32 v[34:35], v[34:35], v[70:71] op_sel_hi:[1,0]
	v_pk_mul_f32 v[36:37], v[36:37], v[70:71] op_sel_hi:[1,0]
	v_pk_mul_f32 v[38:39], v[38:39], v[70:71] op_sel_hi:[1,0]
	v_pk_mul_f32 v[40:41], v[40:41], v[70:71] op_sel_hi:[1,0]
	v_pk_mul_f32 v[42:43], v[42:43], v[70:71] op_sel_hi:[1,0]
	v_pk_mul_f32 v[18:19], v[18:19], v[70:71] op_sel_hi:[1,0]
	v_pk_mul_f32 v[20:21], v[20:21], v[70:71] op_sel_hi:[1,0]
	v_pk_mul_f32 v[22:23], v[22:23], v[70:71] op_sel_hi:[1,0]
	v_pk_mul_f32 v[24:25], v[24:25], v[70:71] op_sel_hi:[1,0]
	v_pk_mul_f32 v[26:27], v[26:27], v[70:71] op_sel_hi:[1,0]
	v_pk_mul_f32 v[2:3], v[2:3], v[70:71] op_sel_hi:[1,0]
	v_pk_mul_f32 v[4:5], v[4:5], v[70:71] op_sel_hi:[1,0]
	v_pk_mul_f32 v[6:7], v[6:7], v[70:71] op_sel_hi:[1,0]
	v_pk_mul_f32 v[8:9], v[8:9], v[70:71] op_sel_hi:[1,0]
	v_pk_mul_f32 v[10:11], v[10:11], v[70:71] op_sel_hi:[1,0]
	s_waitcnt vmcnt(1)
	v_and_b32_e32 v79, 0xffff0000, v76
	v_lshlrev_b32_e32 v78, 16, v76
	v_mul_f32_e32 v76, 0xbfb8aa3b, v78
	s_waitcnt vmcnt(0)
	v_pk_mul_f32 v[50:51], v[66:67], v[50:51]
	v_mul_f32_e32 v66, 0xbfb8aa3b, v79
	v_exp_f32_e32 v76, v76
	v_exp_f32_e32 v66, v66
	v_pk_mul_f32 v[52:53], v[68:69], v[52:53]
	v_add_f32_e32 v76, 1.0, v76
	v_add_f32_e32 v66, 1.0, v66
	v_rcp_f32_e32 v80, v76
	v_rcp_f32_e32 v81, v66
	s_nop 0
	v_pk_mul_f32 v[66:67], v[80:81], v[78:79]
	s_nop 0
	v_pk_mul_f32 v[66:67], v[66:67], v[50:51]
	v_and_b32_e32 v51, 0xffff0000, v77
	v_lshlrev_b32_e32 v50, 16, v77
	v_mul_f32_e32 v76, 0xbfb8aa3b, v50
	v_mul_f32_e32 v68, 0xbfb8aa3b, v51
	v_exp_f32_e32 v76, v76
	v_exp_f32_e32 v68, v68
	v_cvt_pk_bf16_f32 v66, v66, v67
	v_add_f32_e32 v76, 1.0, v76
	v_add_f32_e32 v68, 1.0, v68
	v_rcp_f32_e32 v76, v76
	v_rcp_f32_e32 v77, v68
	v_lshl_add_u64 v[68:69], v[74:75], 0, v[0:1]
	v_pk_mul_f32 v[50:51], v[76:77], v[50:51]
	s_nop 0
	v_pk_mul_f32 v[52:53], v[50:51], v[52:53]
	v_lshl_add_u64 v[50:51], v[68:69], 0, s[0:1]
	s_mov_b32 s0, 0x23081000
	v_cvt_pk_bf16_f32 v67, v52, v53
	v_add_co_u32_e32 v52, vcc, s0, v68
	v_readlane_b32 s0, v252, 43
	s_nop 0
	v_addc_co_u32_e32 v53, vcc, 0, v69, vcc
	global_store_dwordx2 v[52:53], v[66:67], off offset:2048
	global_load_dwordx2 v[52:53], v[72:73], off offset:16
	s_nop 0
	global_load_dwordx4 v[66:69], v71, s[46:47] offset:32
	v_add_u32_e32 v115, s0, v115
	s_movk_i32 s0, 0x7ff
	v_cmp_lt_i32_e32 vcc, s0, v115
	s_or_b64 s[52:53], vcc, s[52:53]
	v_readlane_b32 s1, v252, 44
	s_waitcnt vmcnt(1)
; DI float bf2f(bf16_t v) { return __uint_as_float(((unsigned)v) << 16); }
; DI float frcp(float x) { return __builtin_amdgcn_rcpf(x); }
; DI void st_bf16x4(bf16_t* p, f32x4 v) { u32x2 o; o.x = pk2e(v[0], v[1]); o.y = pk2e(v[2], v[3]); *(u32x2*)p = o; }
; DI void hgrn_out_task(const Params& p, int e, int bh, int c, int tt) {
;     ...
; #pragma unroll
;   for (int vt = 0; vt < 4; ++vt)
; #pragma unroll
;     for (int q = 0; q < 4; ++q) {
;       const int d0 = vt * 32 + q * 8 + 4 * g;
;       const s16x4 gv = *(const s16x4*)(hg + d0); const f32x4 gn = *(const f32x4*)(og + d0);
;       f32x4 v;
; #pragma unroll
;       for (int e2 = 0; e2 < 4; ++e2) { const float gg = bf2f((bf16_t)gv[e2]); v[e2] = o[vt][q * 4 + e2] * rs * gn[e2] * (gg * frcp(1.f + __expf(-gg))); }
;       st_bf16x4(orow + d0, v);
;     }
	v_lshlrev_b32_e32 v74, 16, v52
	v_mul_f32_e32 v0, 0xbfb8aa3b, v74
	v_exp_f32_e32 v0, v0
	v_and_b32_e32 v75, 0xffff0000, v52
	s_waitcnt vmcnt(0)
	v_pk_mul_f32 v[54:55], v[66:67], v[54:55]
	v_pk_mul_f32 v[56:57], v[68:69], v[56:57]
	v_add_f32_e32 v0, 1.0, v0
	v_rcp_f32_e32 v76, v0
	v_mul_f32_e32 v0, 0xbfb8aa3b, v75
	v_exp_f32_e32 v0, v0
	s_nop 0
	v_add_f32_e32 v0, 1.0, v0
	v_rcp_f32_e32 v77, v0
	s_nop 0
	v_pk_mul_f32 v[66:67], v[76:77], v[74:75]
	s_nop 0
	v_pk_mul_f32 v[54:55], v[54:55], v[66:67]
	v_lshlrev_b32_e32 v66, 16, v53
	v_mul_f32_e32 v0, 0xbfb8aa3b, v66
	v_exp_f32_e32 v0, v0
	v_and_b32_e32 v67, 0xffff0000, v53
	v_cvt_pk_bf16_f32 v54, v54, v55
	v_add_f32_e32 v0, 1.0, v0
	v_rcp_f32_e32 v52, v0
	v_mul_f32_e32 v0, 0xbfb8aa3b, v67
	v_exp_f32_e32 v0, v0
	s_nop 0
	v_add_f32_e32 v0, 1.0, v0
	v_rcp_f32_e32 v53, v0
	s_nop 0
	v_pk_mul_f32 v[52:53], v[52:53], v[66:67]
	s_nop 0
	v_pk_mul_f32 v[52:53], v[56:57], v[52:53]
	s_nop 0
	v_cvt_pk_bf16_f32 v55, v52, v53
	global_store_dwordx2 v[50:51], v[54:55], off offset:16
	global_load_dwordx2 v[56:57], v[72:73], off offset:32
	s_nop 0
	global_load_dwordx4 v[52:55], v71, s[46:47] offset:64
	s_waitcnt vmcnt(1)
	v_lshlrev_b32_e32 v66, 16, v56
	v_mul_f32_e32 v0, 0xbfb8aa3b, v66
	v_exp_f32_e32 v0, v0
	v_and_b32_e32 v67, 0xffff0000, v56
	s_waitcnt vmcnt(0)
	v_pk_mul_f32 v[52:53], v[52:53], v[58:59]
	v_pk_mul_f32 v[54:55], v[54:55], v[60:61]
	v_add_f32_e32 v0, 1.0, v0
	v_rcp_f32_e32 v68, v0
	v_mul_f32_e32 v0, 0xbfb8aa3b, v67
	v_exp_f32_e32 v0, v0
	s_nop 0
	v_add_f32_e32 v0, 1.0, v0
	v_rcp_f32_e32 v69, v0
	s_nop 0
	v_pk_mul_f32 v[58:59], v[68:69], v[66:67]
	s_nop 0
	v_pk_mul_f32 v[52:53], v[52:53], v[58:59]
	v_lshlrev_b32_e32 v58, 16, v57
	v_mul_f32_e32 v0, 0xbfb8aa3b, v58
	v_exp_f32_e32 v0, v0
	v_and_b32_e32 v59, 0xffff0000, v57
	v_cvt_pk_bf16_f32 v52, v52, v53
	v_add_f32_e32 v0, 1.0, v0
	v_rcp_f32_e32 v56, v0
	v_mul_f32_e32 v0, 0xbfb8aa3b, v59
	v_exp_f32_e32 v0, v0
	s_nop 0
	v_add_f32_e32 v0, 1.0, v0
	v_rcp_f32_e32 v57, v0
	s_nop 0
	v_pk_mul_f32 v[56:57], v[56:57], v[58:59]
	s_nop 0
	v_pk_mul_f32 v[54:55], v[54:55], v[56:57]
	s_nop 0
	v_cvt_pk_bf16_f32 v53, v54, v55
	global_store_dwordx2 v[50:51], v[52:53], off offset:32
	global_load_dwordx2 v[56:57], v[72:73], off offset:48
	s_nop 0
	global_load_dwordx4 v[52:55], v71, s[46:47] offset:96
	s_waitcnt vmcnt(1)
	v_lshlrev_b32_e32 v58, 16, v56
	v_mul_f32_e32 v0, 0xbfb8aa3b, v58
	v_exp_f32_e32 v0, v0
	v_and_b32_e32 v59, 0xffff0000, v56
	s_waitcnt vmcnt(0)
	v_pk_mul_f32 v[52:53], v[62:63], v[52:53]
	v_add_f32_e32 v0, 1.0, v0
	v_rcp_f32_e32 v60, v0
	v_mul_f32_e32 v0, 0xbfb8aa3b, v59
	v_exp_f32_e32 v0, v0
	s_nop 0
	v_add_f32_e32 v0, 1.0, v0
	v_rcp_f32_e32 v61, v0
	s_nop 0
	v_pk_mul_f32 v[58:59], v[60:61], v[58:59]
	s_nop 0
	v_pk_mul_f32 v[52:53], v[52:53], v[58:59]
	v_lshlrev_b32_e32 v58, 16, v57
	v_mul_f32_e32 v0, 0xbfb8aa3b, v58
	v_exp_f32_e32 v0, v0
	v_and_b32_e32 v59, 0xffff0000, v57
	v_pk_mul_f32 v[60:61], v[64:65], v[70:71] op_sel_hi:[1,0]
	v_cvt_pk_bf16_f32 v52, v52, v53
	v_add_f32_e32 v0, 1.0, v0
	v_rcp_f32_e32 v56, v0
	v_mul_f32_e32 v0, 0xbfb8aa3b, v59
	v_exp_f32_e32 v0, v0
	v_pk_mul_f32 v[54:55], v[60:61], v[54:55]
	v_add_f32_e32 v0, 1.0, v0
	v_rcp_f32_e32 v57, v0
	s_nop 0
	v_pk_mul_f32 v[56:57], v[56:57], v[58:59]
	s_nop 0
	v_pk_mul_f32 v[54:55], v[54:55], v[56:57]
	s_nop 0
	v_cvt_pk_bf16_f32 v53, v54, v55
	global_store_dwordx2 v[50:51], v[52:53], off offset:48
	global_load_dwordx2 v[56:57], v[72:73], off offset:64
	s_nop 0
	global_load_dwordx4 v[52:55], v71, s[46:47] offset:128
	s_waitcnt vmcnt(1)
	v_lshlrev_b32_e32 v58, 16, v56
	v_mul_f32_e32 v0, 0xbfb8aa3b, v58
	v_exp_f32_e32 v0, v0
	v_and_b32_e32 v59, 0xffff0000, v56
	s_waitcnt vmcnt(0)
	v_pk_mul_f32 v[34:35], v[34:35], v[52:53]
	v_pk_mul_f32 v[36:37], v[36:37], v[54:55]
	v_add_f32_e32 v0, 1.0, v0
	v_rcp_f32_e32 v60, v0
	v_mul_f32_e32 v0, 0xbfb8aa3b, v59
	v_exp_f32_e32 v0, v0
	s_nop 0
	v_add_f32_e32 v0, 1.0, v0
	v_rcp_f32_e32 v61, v0
	s_nop 0
	v_pk_mul_f32 v[52:53], v[60:61], v[58:59]
	s_nop 0
	v_pk_mul_f32 v[34:35], v[34:35], v[52:53]
	v_lshlrev_b32_e32 v52, 16, v57
	v_mul_f32_e32 v0, 0xbfb8aa3b, v52
	v_exp_f32_e32 v0, v0
	v_and_b32_e32 v53, 0xffff0000, v57
	v_cvt_pk_bf16_f32 v34, v34, v35
	v_add_f32_e32 v0, 1.0, v0
	v_rcp_f32_e32 v56, v0
	v_mul_f32_e32 v0, 0xbfb8aa3b, v53
	v_exp_f32_e32 v0, v0
	s_nop 0
	v_add_f32_e32 v0, 1.0, v0
	v_rcp_f32_e32 v57, v0
	s_nop 0
	v_pk_mul_f32 v[52:53], v[56:57], v[52:53]
	s_nop 0
	v_pk_mul_f32 v[36:37], v[36:37], v[52:53]
	s_nop 0
	v_cvt_pk_bf16_f32 v35, v36, v37
	global_store_dwordx2 v[50:51], v[34:35], off offset:64
	global_load_dwordx2 v[52:53], v[72:73], off offset:80
	s_nop 0
	global_load_dwordx4 v[34:37], v71, s[46:47] offset:160
	s_waitcnt vmcnt(1)
	v_lshlrev_b32_e32 v54, 16, v52
	v_mul_f32_e32 v0, 0xbfb8aa3b, v54
	v_exp_f32_e32 v0, v0
	v_and_b32_e32 v55, 0xffff0000, v52
	s_waitcnt vmcnt(0)
	v_pk_mul_f32 v[34:35], v[38:39], v[34:35]
	v_pk_mul_f32 v[36:37], v[40:41], v[36:37]
	v_add_f32_e32 v0, 1.0, v0
	v_rcp_f32_e32 v56, v0
	v_mul_f32_e32 v0, 0xbfb8aa3b, v55
	v_exp_f32_e32 v0, v0
	s_nop 0
	v_add_f32_e32 v0, 1.0, v0
	v_rcp_f32_e32 v57, v0
	s_nop 0
	v_pk_mul_f32 v[38:39], v[56:57], v[54:55]
	s_nop 0
	v_pk_mul_f32 v[34:35], v[34:35], v[38:39]
	v_lshlrev_b32_e32 v38, 16, v53
	v_mul_f32_e32 v0, 0xbfb8aa3b, v38
	v_exp_f32_e32 v0, v0
	v_and_b32_e32 v39, 0xffff0000, v53
	v_cvt_pk_bf16_f32 v34, v34, v35
	v_add_f32_e32 v0, 1.0, v0
	v_rcp_f32_e32 v52, v0
	v_mul_f32_e32 v0, 0xbfb8aa3b, v39
	v_exp_f32_e32 v0, v0
	s_nop 0
	v_add_f32_e32 v0, 1.0, v0
	v_rcp_f32_e32 v53, v0
	s_nop 0
	v_pk_mul_f32 v[38:39], v[52:53], v[38:39]
	s_nop 0
	v_pk_mul_f32 v[36:37], v[36:37], v[38:39]
	s_nop 0
	v_cvt_pk_bf16_f32 v35, v36, v37
	global_store_dwordx2 v[50:51], v[34:35], off offset:80
	global_load_dwordx2 v[38:39], v[72:73], off offset:96
	s_nop 0
	global_load_dwordx4 v[34:37], v71, s[46:47] offset:192
	s_waitcnt vmcnt(1)
; DI float bf2f(bf16_t v) { return __uint_as_float(((unsigned)v) << 16); }
; DI float frcp(float x) { return __builtin_amdgcn_rcpf(x); }
; DI void st_bf16x4(bf16_t* p, f32x4 v) { u32x2 o; o.x = pk2e(v[0], v[1]); o.y = pk2e(v[2], v[3]); *(u32x2*)p = o; }
; DI void hgrn_out_task(const Params& p, int e, int bh, int c, int tt) {
;     ...
; #pragma unroll
;   for (int vt = 0; vt < 4; ++vt)
; #pragma unroll
;     for (int q = 0; q < 4; ++q) {
;       const int d0 = vt * 32 + q * 8 + 4 * g;
;       const s16x4 gv = *(const s16x4*)(hg + d0); const f32x4 gn = *(const f32x4*)(og + d0);
;       f32x4 v;
; #pragma unroll
;       for (int e2 = 0; e2 < 4; ++e2) { const float gg = bf2f((bf16_t)gv[e2]); v[e2] = o[vt][q * 4 + e2] * rs * gn[e2] * (gg * frcp(1.f + __expf(-gg))); }
;       st_bf16x4(orow + d0, v);
;     }
	v_lshlrev_b32_e32 v40, 16, v38
	v_mul_f32_e32 v0, 0xbfb8aa3b, v40
	v_exp_f32_e32 v0, v0
	v_and_b32_e32 v41, 0xffff0000, v38
	s_waitcnt vmcnt(0)
	v_pk_mul_f32 v[34:35], v[42:43], v[34:35]
	v_pk_mul_f32 v[42:43], v[44:45], v[70:71] op_sel_hi:[1,0]
	v_add_f32_e32 v0, 1.0, v0
	v_rcp_f32_e32 v52, v0
	v_mul_f32_e32 v0, 0xbfb8aa3b, v41
	v_exp_f32_e32 v0, v0
	v_pk_mul_f32 v[36:37], v[42:43], v[36:37]
	v_pk_mul_f32 v[44:45], v[46:47], v[70:71] op_sel_hi:[1,0]
	v_add_f32_e32 v0, 1.0, v0
	v_rcp_f32_e32 v53, v0
	s_nop 0
	v_pk_mul_f32 v[40:41], v[52:53], v[40:41]
	s_nop 0
	v_pk_mul_f32 v[34:35], v[34:35], v[40:41]
	v_lshlrev_b32_e32 v40, 16, v39
	v_mul_f32_e32 v0, 0xbfb8aa3b, v40
	v_exp_f32_e32 v0, v0
	v_and_b32_e32 v41, 0xffff0000, v39
	v_cvt_pk_bf16_f32 v34, v34, v35
	v_add_f32_e32 v0, 1.0, v0
	v_rcp_f32_e32 v38, v0
	v_mul_f32_e32 v0, 0xbfb8aa3b, v41
	v_exp_f32_e32 v0, v0
	s_nop 0
	v_add_f32_e32 v0, 1.0, v0
	v_rcp_f32_e32 v39, v0
	s_nop 0
	v_pk_mul_f32 v[38:39], v[38:39], v[40:41]
	s_nop 0
	v_pk_mul_f32 v[36:37], v[36:37], v[38:39]
	s_nop 0
	v_cvt_pk_bf16_f32 v35, v36, v37
	global_store_dwordx2 v[50:51], v[34:35], off offset:96
	global_load_dwordx2 v[38:39], v[72:73], off offset:112
	s_nop 0
	global_load_dwordx4 v[34:37], v71, s[46:47] offset:224
	s_waitcnt vmcnt(1)
	v_lshlrev_b32_e32 v40, 16, v38
	v_mul_f32_e32 v0, 0xbfb8aa3b, v40
	v_exp_f32_e32 v0, v0
	v_and_b32_e32 v41, 0xffff0000, v38
	s_waitcnt vmcnt(0)
	v_pk_mul_f32 v[34:35], v[44:45], v[34:35]
	v_add_f32_e32 v0, 1.0, v0
	v_rcp_f32_e32 v42, v0
	v_mul_f32_e32 v0, 0xbfb8aa3b, v41
	v_exp_f32_e32 v0, v0
	s_nop 0
	v_add_f32_e32 v0, 1.0, v0
	v_rcp_f32_e32 v43, v0
	s_nop 0
	v_pk_mul_f32 v[40:41], v[42:43], v[40:41]
	s_nop 0
	v_pk_mul_f32 v[34:35], v[34:35], v[40:41]
	v_lshlrev_b32_e32 v40, 16, v39
	v_mul_f32_e32 v0, 0xbfb8aa3b, v40
	v_exp_f32_e32 v0, v0
	v_and_b32_e32 v41, 0xffff0000, v39
	v_pk_mul_f32 v[42:43], v[48:49], v[70:71] op_sel_hi:[1,0]
	v_cvt_pk_bf16_f32 v34, v34, v35
	v_add_f32_e32 v0, 1.0, v0
	v_rcp_f32_e32 v38, v0
	v_mul_f32_e32 v0, 0xbfb8aa3b, v41
	v_exp_f32_e32 v0, v0
	v_pk_mul_f32 v[36:37], v[42:43], v[36:37]
	v_add_f32_e32 v0, 1.0, v0
	v_rcp_f32_e32 v39, v0
	s_nop 0
	v_pk_mul_f32 v[38:39], v[38:39], v[40:41]
	s_nop 0
	v_pk_mul_f32 v[36:37], v[36:37], v[38:39]
	s_nop 0
	v_cvt_pk_bf16_f32 v35, v36, v37
	global_store_dwordx2 v[50:51], v[34:35], off offset:112
	global_load_dwordx2 v[38:39], v[72:73], off offset:128
	s_nop 0
	global_load_dwordx4 v[34:37], v71, s[46:47] offset:256
	s_waitcnt vmcnt(1)
	v_lshlrev_b32_e32 v40, 16, v38
	v_mul_f32_e32 v0, 0xbfb8aa3b, v40
	v_exp_f32_e32 v0, v0
	v_and_b32_e32 v41, 0xffff0000, v38
	s_waitcnt vmcnt(0)
	v_pk_mul_f32 v[18:19], v[18:19], v[34:35]
	v_pk_mul_f32 v[20:21], v[20:21], v[36:37]
	v_add_f32_e32 v0, 1.0, v0
	v_rcp_f32_e32 v42, v0
	v_mul_f32_e32 v0, 0xbfb8aa3b, v41
	v_exp_f32_e32 v0, v0
	s_nop 0
	v_add_f32_e32 v0, 1.0, v0
	v_rcp_f32_e32 v43, v0
	s_nop 0
	v_pk_mul_f32 v[34:35], v[42:43], v[40:41]
	s_nop 0
	v_pk_mul_f32 v[18:19], v[18:19], v[34:35]
	v_lshlrev_b32_e32 v34, 16, v39
	v_mul_f32_e32 v0, 0xbfb8aa3b, v34
	v_exp_f32_e32 v0, v0
	v_and_b32_e32 v35, 0xffff0000, v39
	v_cvt_pk_bf16_f32 v18, v18, v19
	v_add_f32_e32 v0, 1.0, v0
	v_rcp_f32_e32 v38, v0
	v_mul_f32_e32 v0, 0xbfb8aa3b, v35
	v_exp_f32_e32 v0, v0
	s_nop 0
	v_add_f32_e32 v0, 1.0, v0
	v_rcp_f32_e32 v39, v0
	s_nop 0
	v_pk_mul_f32 v[34:35], v[38:39], v[34:35]
	s_nop 0
	v_pk_mul_f32 v[20:21], v[20:21], v[34:35]
	s_nop 0
	v_cvt_pk_bf16_f32 v19, v20, v21
	global_store_dwordx2 v[50:51], v[18:19], off offset:128
	global_load_dwordx2 v[34:35], v[72:73], off offset:144
	s_nop 0
	global_load_dwordx4 v[18:21], v71, s[46:47] offset:288
	s_waitcnt vmcnt(1)
	v_lshlrev_b32_e32 v36, 16, v34
	v_mul_f32_e32 v0, 0xbfb8aa3b, v36
	v_exp_f32_e32 v0, v0
	v_and_b32_e32 v37, 0xffff0000, v34
	s_waitcnt vmcnt(0)
	v_pk_mul_f32 v[18:19], v[22:23], v[18:19]
	v_pk_mul_f32 v[20:21], v[24:25], v[20:21]
	v_add_f32_e32 v0, 1.0, v0
	v_rcp_f32_e32 v38, v0
	v_mul_f32_e32 v0, 0xbfb8aa3b, v37
	v_exp_f32_e32 v0, v0
	s_nop 0
	v_add_f32_e32 v0, 1.0, v0
	v_rcp_f32_e32 v39, v0
	s_nop 0
	v_pk_mul_f32 v[22:23], v[38:39], v[36:37]
	s_nop 0
	v_pk_mul_f32 v[18:19], v[18:19], v[22:23]
	v_lshlrev_b32_e32 v22, 16, v35
	v_mul_f32_e32 v0, 0xbfb8aa3b, v22
	v_exp_f32_e32 v0, v0
	v_and_b32_e32 v23, 0xffff0000, v35
	v_cvt_pk_bf16_f32 v18, v18, v19
	v_add_f32_e32 v0, 1.0, v0
	v_rcp_f32_e32 v34, v0
	v_mul_f32_e32 v0, 0xbfb8aa3b, v23
	v_exp_f32_e32 v0, v0
	s_nop 0
	v_add_f32_e32 v0, 1.0, v0
	v_rcp_f32_e32 v35, v0
	s_nop 0
	v_pk_mul_f32 v[22:23], v[34:35], v[22:23]
	s_nop 0
	v_pk_mul_f32 v[20:21], v[20:21], v[22:23]
	s_nop 0
	v_cvt_pk_bf16_f32 v19, v20, v21
	global_store_dwordx2 v[50:51], v[18:19], off offset:144
	global_load_dwordx2 v[22:23], v[72:73], off offset:160
	s_nop 0
	global_load_dwordx4 v[18:21], v71, s[46:47] offset:320
	s_waitcnt vmcnt(1)
	v_lshlrev_b32_e32 v24, 16, v22
	v_mul_f32_e32 v0, 0xbfb8aa3b, v24
	v_exp_f32_e32 v0, v0
	v_and_b32_e32 v25, 0xffff0000, v22
	s_waitcnt vmcnt(0)
	v_pk_mul_f32 v[18:19], v[26:27], v[18:19]
	v_pk_mul_f32 v[26:27], v[28:29], v[70:71] op_sel_hi:[1,0]
	v_add_f32_e32 v0, 1.0, v0
	v_rcp_f32_e32 v34, v0
	v_mul_f32_e32 v0, 0xbfb8aa3b, v25
	v_exp_f32_e32 v0, v0
	v_pk_mul_f32 v[20:21], v[26:27], v[20:21]
	v_pk_mul_f32 v[28:29], v[30:31], v[70:71] op_sel_hi:[1,0]
	v_add_f32_e32 v0, 1.0, v0
	v_rcp_f32_e32 v35, v0
	s_nop 0
	v_pk_mul_f32 v[24:25], v[34:35], v[24:25]
	s_nop 0
	v_pk_mul_f32 v[18:19], v[18:19], v[24:25]
	v_lshlrev_b32_e32 v24, 16, v23
	v_mul_f32_e32 v0, 0xbfb8aa3b, v24
	v_exp_f32_e32 v0, v0
	v_and_b32_e32 v25, 0xffff0000, v23
	v_cvt_pk_bf16_f32 v18, v18, v19
	v_add_f32_e32 v0, 1.0, v0
	v_rcp_f32_e32 v22, v0
	v_mul_f32_e32 v0, 0xbfb8aa3b, v25
	v_exp_f32_e32 v0, v0
	s_nop 0
	v_add_f32_e32 v0, 1.0, v0
	v_rcp_f32_e32 v23, v0
	s_nop 0
	v_pk_mul_f32 v[22:23], v[22:23], v[24:25]
	s_nop 0
	v_pk_mul_f32 v[20:21], v[20:21], v[22:23]
	s_nop 0
	v_cvt_pk_bf16_f32 v19, v20, v21
	global_store_dwordx2 v[50:51], v[18:19], off offset:160
	global_load_dwordx2 v[22:23], v[72:73], off offset:176
	s_nop 0
	global_load_dwordx4 v[18:21], v71, s[46:47] offset:352
	s_waitcnt vmcnt(1)
; DI float bf2f(bf16_t v) { return __uint_as_float(((unsigned)v) << 16); }
; DI float frcp(float x) { return __builtin_amdgcn_rcpf(x); }
; DI void st_bf16x4(bf16_t* p, f32x4 v) { u32x2 o; o.x = pk2e(v[0], v[1]); o.y = pk2e(v[2], v[3]); *(u32x2*)p = o; }
; DI void hgrn_out_task(const Params& p, int e, int bh, int c, int tt) {
;     ...
; #pragma unroll
;   for (int vt = 0; vt < 4; ++vt)
; #pragma unroll
;     for (int q = 0; q < 4; ++q) {
;       const int d0 = vt * 32 + q * 8 + 4 * g;
;       const s16x4 gv = *(const s16x4*)(hg + d0); const f32x4 gn = *(const f32x4*)(og + d0);
;       f32x4 v;
; #pragma unroll
;       for (int e2 = 0; e2 < 4; ++e2) { const float gg = bf2f((bf16_t)gv[e2]); v[e2] = o[vt][q * 4 + e2] * rs * gn[e2] * (gg * frcp(1.f + __expf(-gg))); }
;       st_bf16x4(orow + d0, v);
;     }
	v_lshlrev_b32_e32 v24, 16, v22
	v_mul_f32_e32 v0, 0xbfb8aa3b, v24
	v_exp_f32_e32 v0, v0
	v_and_b32_e32 v25, 0xffff0000, v22
	s_waitcnt vmcnt(0)
	v_pk_mul_f32 v[18:19], v[28:29], v[18:19]
	v_add_f32_e32 v0, 1.0, v0
	v_rcp_f32_e32 v26, v0
	v_mul_f32_e32 v0, 0xbfb8aa3b, v25
	v_exp_f32_e32 v0, v0
	s_nop 0
	v_add_f32_e32 v0, 1.0, v0
	v_rcp_f32_e32 v27, v0
	s_nop 0
	v_pk_mul_f32 v[24:25], v[26:27], v[24:25]
	s_nop 0
	v_pk_mul_f32 v[18:19], v[18:19], v[24:25]
	v_lshlrev_b32_e32 v24, 16, v23
	v_mul_f32_e32 v0, 0xbfb8aa3b, v24
	v_exp_f32_e32 v0, v0
	v_and_b32_e32 v25, 0xffff0000, v23
	v_pk_mul_f32 v[26:27], v[32:33], v[70:71] op_sel_hi:[1,0]
	v_cvt_pk_bf16_f32 v18, v18, v19
	v_add_f32_e32 v0, 1.0, v0
	v_rcp_f32_e32 v22, v0
	v_mul_f32_e32 v0, 0xbfb8aa3b, v25
	v_exp_f32_e32 v0, v0
	v_pk_mul_f32 v[20:21], v[26:27], v[20:21]
	v_add_f32_e32 v0, 1.0, v0
	v_rcp_f32_e32 v23, v0
	s_nop 0
	v_pk_mul_f32 v[22:23], v[22:23], v[24:25]
	s_nop 0
	v_pk_mul_f32 v[20:21], v[20:21], v[22:23]
	s_nop 0
	v_cvt_pk_bf16_f32 v19, v20, v21
	global_store_dwordx2 v[50:51], v[18:19], off offset:176
	global_load_dwordx2 v[22:23], v[72:73], off offset:192
	s_nop 0
	global_load_dwordx4 v[18:21], v71, s[46:47] offset:384
	s_waitcnt vmcnt(1)
	v_lshlrev_b32_e32 v24, 16, v22
	v_mul_f32_e32 v0, 0xbfb8aa3b, v24
	v_exp_f32_e32 v0, v0
	v_and_b32_e32 v25, 0xffff0000, v22
	s_waitcnt vmcnt(0)
	v_pk_mul_f32 v[2:3], v[2:3], v[18:19]
	v_pk_mul_f32 v[4:5], v[4:5], v[20:21]
	v_add_f32_e32 v0, 1.0, v0
	v_rcp_f32_e32 v26, v0
	v_mul_f32_e32 v0, 0xbfb8aa3b, v25
	v_exp_f32_e32 v0, v0
	s_nop 0
	v_add_f32_e32 v0, 1.0, v0
	v_rcp_f32_e32 v27, v0
	s_nop 0
	v_pk_mul_f32 v[18:19], v[26:27], v[24:25]
	s_nop 0
	v_pk_mul_f32 v[2:3], v[2:3], v[18:19]
	v_lshlrev_b32_e32 v18, 16, v23
	v_mul_f32_e32 v0, 0xbfb8aa3b, v18
	v_exp_f32_e32 v0, v0
	v_and_b32_e32 v19, 0xffff0000, v23
	v_cvt_pk_bf16_f32 v2, v2, v3
	v_add_f32_e32 v0, 1.0, v0
	v_rcp_f32_e32 v22, v0
	v_mul_f32_e32 v0, 0xbfb8aa3b, v19
	v_exp_f32_e32 v0, v0
	s_nop 0
	v_add_f32_e32 v0, 1.0, v0
	v_rcp_f32_e32 v23, v0
	s_nop 0
	v_pk_mul_f32 v[18:19], v[22:23], v[18:19]
	s_nop 0
	v_pk_mul_f32 v[4:5], v[4:5], v[18:19]
	s_nop 0
	v_cvt_pk_bf16_f32 v3, v4, v5
	global_store_dwordx2 v[50:51], v[2:3], off offset:192
	global_load_dwordx2 v[18:19], v[72:73], off offset:208
	s_nop 0
	global_load_dwordx4 v[2:5], v71, s[46:47] offset:416
	s_waitcnt vmcnt(1)
	v_lshlrev_b32_e32 v20, 16, v18
	v_mul_f32_e32 v0, 0xbfb8aa3b, v20
	v_exp_f32_e32 v0, v0
	v_and_b32_e32 v21, 0xffff0000, v18
	s_waitcnt vmcnt(0)
	v_pk_mul_f32 v[2:3], v[6:7], v[2:3]
	v_pk_mul_f32 v[4:5], v[8:9], v[4:5]
	v_add_f32_e32 v0, 1.0, v0
	v_rcp_f32_e32 v22, v0
	v_mul_f32_e32 v0, 0xbfb8aa3b, v21
	v_exp_f32_e32 v0, v0
	s_nop 0
	v_add_f32_e32 v0, 1.0, v0
	v_rcp_f32_e32 v23, v0
	s_nop 0
	v_pk_mul_f32 v[6:7], v[22:23], v[20:21]
	s_nop 0
	v_pk_mul_f32 v[2:3], v[2:3], v[6:7]
	v_lshlrev_b32_e32 v6, 16, v19
	v_mul_f32_e32 v0, 0xbfb8aa3b, v6
	v_exp_f32_e32 v0, v0
	v_and_b32_e32 v7, 0xffff0000, v19
	v_cvt_pk_bf16_f32 v2, v2, v3
	v_add_f32_e32 v0, 1.0, v0
	v_rcp_f32_e32 v18, v0
	v_mul_f32_e32 v0, 0xbfb8aa3b, v7
	v_exp_f32_e32 v0, v0
	s_nop 0
	v_add_f32_e32 v0, 1.0, v0
	v_rcp_f32_e32 v19, v0
	s_nop 0
	v_pk_mul_f32 v[6:7], v[18:19], v[6:7]
	s_nop 0
	v_pk_mul_f32 v[4:5], v[4:5], v[6:7]
	s_nop 0
	v_cvt_pk_bf16_f32 v3, v4, v5
	global_store_dwordx2 v[50:51], v[2:3], off offset:208
	global_load_dwordx2 v[6:7], v[72:73], off offset:224
	s_nop 0
	global_load_dwordx4 v[2:5], v71, s[46:47] offset:448
	s_waitcnt vmcnt(1)
	v_lshlrev_b32_e32 v8, 16, v6
	v_mul_f32_e32 v0, 0xbfb8aa3b, v8
	v_exp_f32_e32 v0, v0
	v_and_b32_e32 v9, 0xffff0000, v6
	s_waitcnt vmcnt(0)
	v_pk_mul_f32 v[2:3], v[10:11], v[2:3]
	v_pk_mul_f32 v[10:11], v[12:13], v[70:71] op_sel_hi:[1,0]
	v_add_f32_e32 v0, 1.0, v0
	v_rcp_f32_e32 v18, v0
	v_mul_f32_e32 v0, 0xbfb8aa3b, v9
	v_exp_f32_e32 v0, v0
	v_pk_mul_f32 v[4:5], v[10:11], v[4:5]
	v_pk_mul_f32 v[12:13], v[14:15], v[70:71] op_sel_hi:[1,0]
	v_add_f32_e32 v0, 1.0, v0
	v_rcp_f32_e32 v19, v0
	s_nop 0
	v_pk_mul_f32 v[8:9], v[18:19], v[8:9]
	s_nop 0
	v_pk_mul_f32 v[2:3], v[2:3], v[8:9]
	v_lshlrev_b32_e32 v8, 16, v7
	v_mul_f32_e32 v0, 0xbfb8aa3b, v8
	v_exp_f32_e32 v0, v0
	v_and_b32_e32 v9, 0xffff0000, v7
	v_cvt_pk_bf16_f32 v2, v2, v3
	v_add_f32_e32 v0, 1.0, v0
	v_rcp_f32_e32 v6, v0
	v_mul_f32_e32 v0, 0xbfb8aa3b, v9
	v_exp_f32_e32 v0, v0
	s_nop 0
	v_add_f32_e32 v0, 1.0, v0
	v_rcp_f32_e32 v7, v0
	s_nop 0
	v_pk_mul_f32 v[6:7], v[6:7], v[8:9]
	s_nop 0
	v_pk_mul_f32 v[4:5], v[4:5], v[6:7]
	s_nop 0
	v_cvt_pk_bf16_f32 v3, v4, v5
	global_store_dwordx2 v[50:51], v[2:3], off offset:224
	global_load_dwordx2 v[6:7], v[72:73], off offset:240
	s_nop 0
	global_load_dwordx4 v[2:5], v71, s[46:47] offset:480
	s_waitcnt vmcnt(1)
	v_lshlrev_b32_e32 v8, 16, v6
	v_mul_f32_e32 v0, 0xbfb8aa3b, v8
	v_exp_f32_e32 v0, v0
	v_and_b32_e32 v9, 0xffff0000, v6
	s_waitcnt vmcnt(0)
	v_pk_mul_f32 v[2:3], v[12:13], v[2:3]
	v_add_f32_e32 v0, 1.0, v0
	v_rcp_f32_e32 v10, v0
	v_mul_f32_e32 v0, 0xbfb8aa3b, v9
	v_exp_f32_e32 v0, v0
	s_nop 0
	v_add_f32_e32 v0, 1.0, v0
	v_rcp_f32_e32 v11, v0
	s_nop 0
	v_pk_mul_f32 v[8:9], v[10:11], v[8:9]
	s_nop 0
	v_pk_mul_f32 v[2:3], v[2:3], v[8:9]
	v_lshlrev_b32_e32 v8, 16, v7
	v_mul_f32_e32 v0, 0xbfb8aa3b, v8
	v_exp_f32_e32 v0, v0
	v_and_b32_e32 v9, 0xffff0000, v7
	v_pk_mul_f32 v[10:11], v[16:17], v[70:71] op_sel_hi:[1,0]
	v_cvt_pk_bf16_f32 v2, v2, v3
	v_add_f32_e32 v0, 1.0, v0
	v_rcp_f32_e32 v6, v0
	v_mul_f32_e32 v0, 0xbfb8aa3b, v9
	v_exp_f32_e32 v0, v0
	v_pk_mul_f32 v[4:5], v[10:11], v[4:5]
	v_add_f32_e32 v0, 1.0, v0
	v_rcp_f32_e32 v7, v0
	s_nop 0
	v_pk_mul_f32 v[6:7], v[6:7], v[8:9]
	s_nop 0
	v_pk_mul_f32 v[4:5], v[4:5], v[6:7]
	s_nop 0
	v_cvt_pk_bf16_f32 v3, v4, v5
	global_store_dwordx2 v[50:51], v[2:3], off offset:240
	s_andn2_b64 exec, exec, s[52:53]
	s_cbranch_execnz .LBB0_282
